# SwiGLU epilogue stores via in-wave LDS transposition so 4 neighbouring lanes write one 64B segment (plus the tile-transition barrier change)
# baseline (speedup 1.0000x reference)
.LBB0_470:
	s_lshl_b32 s6, s6, 5
	s_and_b32 s22, s6, 0x60
	s_mov_b64 s[6:7], 0x80
	s_add_i32 m0, s41, 0x18000
	v_lshl_add_u64 v[6:7], v[6:7], 0, s[6:7]
	s_lshl_b32 s11, s10, 13
	s_lshl_b32 s23, s22, 7
	s_waitcnt vmcnt(2)
	s_barrier
	global_load_lds_dwordx4 v[6:7], off
	v_lshl_add_u64 v[4:5], v[4:5], 0, s[6:7]
	s_add_i32 m0, s41, 0x1a000
	s_add_i32 s63, s41, 0x8000
	s_add_i32 s64, s41, 0xa000
	global_load_lds_dwordx4 v[4:5], off
	v_lshl_add_u64 v[0:1], v[0:1], 0, s[6:7]
	s_mov_b32 m0, s63
	s_add_u32 s8, s48, 0x40080
	global_load_lds_dwordx4 v[0:1], off
	v_lshl_add_u64 v[0:1], v[2:3], 0, s[6:7]
	s_mov_b32 m0, s64
	s_addc_u32 s9, s49, 0
	global_load_lds_dwordx4 v[0:1], off
	s_add_i32 m0, s41, 0x1c000
	v_lshl_add_u64 v[0:1], s[8:9], 0, v[136:137]
	global_load_lds_dwordx4 v[0:1], off
	v_lshl_add_u64 v[0:1], s[8:9], 0, v[132:133]
	s_add_i32 m0, s41, 0x1e000
	s_sext_i32_i16 s13, s4
	global_load_lds_dwordx4 v[0:1], off
	v_and_b32_e32 v0, 15, v128
	v_lshlrev_b32_e32 v1, 1, v12
	v_lshl_or_b32 v131, s10, 6, v0
	v_lshl_or_b32 v2, v0, 6, v1
	v_lshlrev_b32_e32 v0, 2, v0
	v_and_b32_e32 v3, 32, v0
	v_bitop3_b32 v2, v2, s11, v3 bitop3:0xde
	v_lshlrev_b32_e32 v3, 6, v128
	s_movk_i32 s4, 0x3c0
	s_cmpk_lt_u32 s5, 0x100
	v_and_or_b32 v1, v3, s4, v1
	s_cselect_b64 s[8:9], -1, 0
	s_lshl_b32 s4, s10, 8
	s_add_i32 s4, s4, 0
	s_add_i32 s4, s4, 0x20000
	v_and_b32_e32 v3, 32, v8
	v_add_u32_e32 v153, s4, v0
	v_lshlrev_b32_e32 v0, 8, v128
	v_bitop3_b32 v152, s23, v1, v3 bitop3:0xf6
	v_and_b32_e32 v0, 0x38000, v0
	v_lshlrev_b32_e32 v1, 11, v13
	v_or3_b32 v0, v10, v0, v1
	v_add_u32_e32 v140, v0, v11
	v_lshlrev_b32_e32 v0, 4, v9
	s_waitcnt vmcnt(6)
	v_and_b32_e32 v0, 0x78000, v0
	v_or3_b32 v0, v10, v0, v1
	s_add_i32 s65, 0, 0x10000
	s_add_i32 s66, 0, 0x14000
	v_mbcnt_lo_u32_b32 v233, -1, 0
	v_mbcnt_hi_u32_b32 v233, -1, v233
	v_lshrrev_b32_e32 v230, 2, v233
	v_and_b32_e32 v131, 0xffffffc0, v131
	v_or_b32_e32 v131, v131, v230
	v_lshrrev_b32_e32 v231, 3, v233
	v_xor_b32_e32 v231, v231, v233
	v_and_b32_e32 v231, 3, v231
	v_lshlrev_b32_e32 v231, 3, v231
	v_or_b32_e32 v154, s22, v231
	v_mov_b32_e32 v235, 0x23000
	v_lshl_add_u32 v235, s91, 10, v235
	v_lshl_add_u32 v231, v233, 4, v235
	v_and_b32_e32 v230, 15, v233
	v_lshrrev_b32_e32 v232, 1, v230
	v_lshrrev_b32_e32 v234, 4, v233
	v_xor_b32_e32 v232, v232, v234
	v_and_b32_e32 v232, 3, v232
	v_lshlrev_b32_e32 v232, 4, v232
	v_lshl_add_u32 v230, v230, 6, v232
	v_add_u32_e32 v230, v235, v230
	v_mov_b32_e32 v141, v137
	v_add_u32_e32 v142, v0, v11
	v_mov_b32_e32 v143, v137
	v_mov_b64_e32 v[144:145], 0xb00
	v_mov_b64_e32 v[146:147], 0xaff
	v_add_u32_e32 v155, s65, v152
	v_add_u32_e32 v157, s66, v152
	v_add_u32_e32 v158, 0, v2
	s_movk_i32 s67, 0x1600
	s_mov_b32 s77, 0
	s_barrier
	s_branch .LBB0_473

.LBB0_479:
	v_lshl_add_u32 v160, s12, 10, v153
	ds_read_b32 v162, v160
	v_lshl_or_b32 v150, s13, 7, v154
	v_lshl_add_u32 v159, s40, 8, v131
	v_ashrrev_i32_e32 v151, 31, v150
	v_mov_b64_e32 v[148:149], s[16:17]
	s_waitcnt lgkmcnt(0)
	v_pk_mul_f32 v[124:125], v[124:125], v[162:163] op_sel_hi:[1,0]
	v_pk_mul_f32 v[126:127], v[126:127], v[162:163] op_sel_hi:[1,0]
	v_pk_mul_f32 v[122:123], v[122:123], v[162:163] op_sel_hi:[1,0]
	v_pk_mul_f32 v[120:121], v[120:121], v[162:163] op_sel_hi:[1,0]
	v_pk_mul_f32 v[118:119], v[118:119], v[162:163] op_sel_hi:[1,0]
	v_pk_mul_f32 v[116:117], v[116:117], v[162:163] op_sel_hi:[1,0]
	v_mul_f32_e32 v161, 0xbfb8aa3b, v124
	v_mul_f32_e32 v163, 0xbfb8aa3b, v125
	v_exp_f32_e32 v161, v161
	v_exp_f32_e32 v163, v163
	v_mad_i64_i32 v[164:165], s[12:13], v159, s67, v[148:149]
	v_lshlrev_b64 v[150:151], 1, v[150:151]
	v_pk_mul_f32 v[166:167], v[114:115], v[162:163] op_sel_hi:[1,0]
	v_add_f32_e32 v114, 1.0, v161
	v_rcp_f32_e32 v161, v114
	v_add_f32_e32 v114, 1.0, v163
	v_rcp_f32_e32 v163, v114
	v_lshl_add_u64 v[164:165], v[164:165], 0, v[150:151]
	s_andn2_b64 vcc, exec, s[4:5]
	s_mov_b64 s[4:5], -1
	v_pk_mul_f32 v[114:115], v[112:113], v[162:163] op_sel_hi:[1,0]
	v_mul_f32_e32 v112, v124, v161
	v_mul_f32_e32 v112, v116, v112
	v_mul_f32_e32 v116, 0xbfb8aa3b, v126
	v_mul_f32_e32 v124, 0xbfb8aa3b, v127
	v_exp_f32_e32 v116, v116
	v_exp_f32_e32 v124, v124
	v_mul_f32_e32 v113, v125, v163
	v_mul_f32_e32 v113, v117, v113
	v_add_f32_e32 v116, 1.0, v116
	v_add_f32_e32 v117, 1.0, v124
	v_rcp_f32_e32 v116, v116
	v_rcp_f32_e32 v117, v117
	v_cvt_pk_bf16_f32 v112, v112, v113
	v_mul_f32_e32 v113, v126, v116
	v_mul_f32_e32 v116, v127, v117
	v_mul_f32_e32 v117, 0xbfb8aa3b, v120
	v_mul_f32_e32 v113, v118, v113
	v_exp_f32_e32 v117, v117
	v_mul_f32_e32 v118, 0xbfb8aa3b, v121
	v_exp_f32_e32 v118, v118
	v_mul_f32_e32 v116, v119, v116
	v_add_f32_e32 v117, 1.0, v117
	v_rcp_f32_e32 v117, v117
	v_add_f32_e32 v118, 1.0, v118
	v_rcp_f32_e32 v118, v118
	v_cvt_pk_bf16_f32 v113, v113, v116
	v_mul_f32_e32 v116, v120, v117
	v_mul_f32_e32 v117, 0xbfb8aa3b, v122
	v_mul_f32_e32 v114, v114, v116
	v_mul_f32_e32 v116, v121, v118
	v_exp_f32_e32 v117, v117
	v_mul_f32_e32 v118, 0xbfb8aa3b, v123
	v_exp_f32_e32 v118, v118
	v_mul_f32_e32 v115, v115, v116
	v_add_f32_e32 v116, 1.0, v117
	v_rcp_f32_e32 v116, v116
	v_add_f32_e32 v117, 1.0, v118
	v_rcp_f32_e32 v117, v117
	v_cvt_pk_bf16_f32 v114, v114, v115
	v_mul_f32_e32 v115, v122, v116
	v_mul_f32_e32 v115, v166, v115
	v_mul_f32_e32 v116, v123, v117
	v_mul_f32_e32 v116, v167, v116
	v_cvt_pk_bf16_f32 v115, v115, v116
	ds_write_b128 v230, v[112:115]
	ds_read_b128 v[232:235], v231
	v_mov_b32_e32 v236, v164
	v_mov_b32_e32 v237, v165
	ds_read_b32 v112, v160 offset:64
	s_nop 0
	v_or_b32_e32 v113, 16, v159
	v_mad_i64_i32 v[114:115], s[12:13], v113, s67, v[148:149]
	s_waitcnt lgkmcnt(0)
	global_store_dwordx4 v[236:237], v[232:235], off
	v_pk_mul_f32 v[108:109], v[108:109], v[112:113] op_sel_hi:[1,0]
	v_pk_mul_f32 v[110:111], v[110:111], v[112:113] op_sel_hi:[1,0]
	v_pk_mul_f32 v[106:107], v[106:107], v[112:113] op_sel_hi:[1,0]
	v_pk_mul_f32 v[104:105], v[104:105], v[112:113] op_sel_hi:[1,0]
	v_pk_mul_f32 v[102:103], v[102:103], v[112:113] op_sel_hi:[1,0]
	v_pk_mul_f32 v[100:101], v[100:101], v[112:113] op_sel_hi:[1,0]
	v_mul_f32_e32 v113, 0xbfb8aa3b, v108
	v_exp_f32_e32 v113, v113
	v_mul_f32_e32 v116, 0xbfb8aa3b, v109
	v_exp_f32_e32 v118, v116
	v_lshl_add_u64 v[114:115], v[114:115], 0, v[150:151]
	v_pk_mul_f32 v[116:117], v[98:99], v[112:113] op_sel_hi:[1,0]
	v_add_f32_e32 v98, 1.0, v113
	v_rcp_f32_e32 v113, v98
	v_add_f32_e32 v98, 1.0, v118
	v_rcp_f32_e32 v118, v98
	v_pk_mul_f32 v[98:99], v[96:97], v[112:113] op_sel_hi:[1,0]
	v_mul_f32_e32 v96, v108, v113
	v_mul_f32_e32 v96, v100, v96
	v_mul_f32_e32 v100, 0xbfb8aa3b, v110
	v_mul_f32_e32 v108, 0xbfb8aa3b, v111
	v_exp_f32_e32 v100, v100
	v_exp_f32_e32 v108, v108
	v_mul_f32_e32 v97, v109, v118
	v_mul_f32_e32 v97, v101, v97
	v_add_f32_e32 v100, 1.0, v100
	v_add_f32_e32 v101, 1.0, v108
	v_rcp_f32_e32 v100, v100
	v_rcp_f32_e32 v101, v101
	v_cvt_pk_bf16_f32 v96, v96, v97
	v_mul_f32_e32 v97, v110, v100
	v_mul_f32_e32 v100, v111, v101
	v_mul_f32_e32 v101, 0xbfb8aa3b, v104
	v_mul_f32_e32 v97, v102, v97
	v_exp_f32_e32 v101, v101
	v_mul_f32_e32 v102, 0xbfb8aa3b, v105
	v_exp_f32_e32 v102, v102
	v_mul_f32_e32 v100, v103, v100
	v_add_f32_e32 v101, 1.0, v101
	v_rcp_f32_e32 v101, v101
	v_add_f32_e32 v102, 1.0, v102
	v_rcp_f32_e32 v102, v102
	v_cvt_pk_bf16_f32 v97, v97, v100
	v_mul_f32_e32 v100, v104, v101
	v_mul_f32_e32 v101, 0xbfb8aa3b, v106
	v_mul_f32_e32 v98, v98, v100
	v_mul_f32_e32 v100, v105, v102
	v_exp_f32_e32 v101, v101
	v_mul_f32_e32 v102, 0xbfb8aa3b, v107
	v_exp_f32_e32 v102, v102
	v_mul_f32_e32 v99, v99, v100
	v_add_f32_e32 v100, 1.0, v101
	v_rcp_f32_e32 v100, v100
	v_add_f32_e32 v101, 1.0, v102
	v_rcp_f32_e32 v101, v101
	v_cvt_pk_bf16_f32 v98, v98, v99
	v_mul_f32_e32 v99, v106, v100
	v_mul_f32_e32 v99, v116, v99
	v_mul_f32_e32 v100, v107, v101
	v_mul_f32_e32 v100, v117, v100
	v_cvt_pk_bf16_f32 v99, v99, v100
	ds_write_b128 v230, v[96:99]
	ds_read_b128 v[232:235], v231
	v_mov_b32_e32 v236, v114
	v_mov_b32_e32 v237, v115
	ds_read_b32 v96, v160 offset:128
	s_nop 0
	v_or_b32_e32 v97, 32, v159
	v_mad_i64_i32 v[98:99], s[12:13], v97, s67, v[148:149]
	s_waitcnt lgkmcnt(0)
	global_store_dwordx4 v[236:237], v[232:235], off
	v_pk_mul_f32 v[92:93], v[92:93], v[96:97] op_sel_hi:[1,0]
	v_pk_mul_f32 v[94:95], v[94:95], v[96:97] op_sel_hi:[1,0]
	v_pk_mul_f32 v[90:91], v[90:91], v[96:97] op_sel_hi:[1,0]
	v_pk_mul_f32 v[88:89], v[88:89], v[96:97] op_sel_hi:[1,0]
	v_pk_mul_f32 v[86:87], v[86:87], v[96:97] op_sel_hi:[1,0]
	v_pk_mul_f32 v[84:85], v[84:85], v[96:97] op_sel_hi:[1,0]
	v_mul_f32_e32 v97, 0xbfb8aa3b, v92
	v_exp_f32_e32 v97, v97
	v_mul_f32_e32 v100, 0xbfb8aa3b, v93
	v_exp_f32_e32 v102, v100
	v_lshl_add_u64 v[98:99], v[98:99], 0, v[150:151]
	v_pk_mul_f32 v[100:101], v[82:83], v[96:97] op_sel_hi:[1,0]
	v_add_f32_e32 v82, 1.0, v97
	v_rcp_f32_e32 v97, v82
	v_add_f32_e32 v82, 1.0, v102
	v_rcp_f32_e32 v102, v82
	v_pk_mul_f32 v[82:83], v[80:81], v[96:97] op_sel_hi:[1,0]
	v_mul_f32_e32 v80, v92, v97
	v_mul_f32_e32 v80, v84, v80
	v_mul_f32_e32 v84, 0xbfb8aa3b, v94
	v_mul_f32_e32 v92, 0xbfb8aa3b, v95
	v_exp_f32_e32 v84, v84
	v_exp_f32_e32 v92, v92
	v_mul_f32_e32 v81, v93, v102
	v_mul_f32_e32 v81, v85, v81
	v_add_f32_e32 v84, 1.0, v84
	v_add_f32_e32 v85, 1.0, v92
	v_rcp_f32_e32 v84, v84
	v_rcp_f32_e32 v85, v85
	v_cvt_pk_bf16_f32 v80, v80, v81
	v_mul_f32_e32 v81, v94, v84
	v_mul_f32_e32 v84, v95, v85
	v_mul_f32_e32 v85, 0xbfb8aa3b, v88
	v_mul_f32_e32 v81, v86, v81
	v_exp_f32_e32 v85, v85
	v_mul_f32_e32 v86, 0xbfb8aa3b, v89
	v_exp_f32_e32 v86, v86
	v_mul_f32_e32 v84, v87, v84
	v_add_f32_e32 v85, 1.0, v85
	v_rcp_f32_e32 v85, v85
	v_add_f32_e32 v86, 1.0, v86
	v_rcp_f32_e32 v86, v86
	v_cvt_pk_bf16_f32 v81, v81, v84
	v_mul_f32_e32 v84, v88, v85
	v_mul_f32_e32 v85, 0xbfb8aa3b, v90
	v_mul_f32_e32 v82, v82, v84
	v_mul_f32_e32 v84, v89, v86
	v_exp_f32_e32 v85, v85
	v_mul_f32_e32 v86, 0xbfb8aa3b, v91
	v_exp_f32_e32 v86, v86
	v_mul_f32_e32 v83, v83, v84
	v_add_f32_e32 v84, 1.0, v85
	v_rcp_f32_e32 v84, v84
	v_add_f32_e32 v85, 1.0, v86
	v_rcp_f32_e32 v85, v85
	v_cvt_pk_bf16_f32 v82, v82, v83
	v_mul_f32_e32 v83, v90, v84
	v_mul_f32_e32 v83, v100, v83
	v_mul_f32_e32 v84, v91, v85
	v_mul_f32_e32 v84, v101, v84
	v_cvt_pk_bf16_f32 v83, v83, v84
	ds_write_b128 v230, v[80:83]
	ds_read_b128 v[232:235], v231
	v_mov_b32_e32 v236, v98
	v_mov_b32_e32 v237, v99
	ds_read_b32 v80, v160 offset:192
	s_nop 0
	v_or_b32_e32 v81, 48, v159
	v_mad_i64_i32 v[82:83], s[12:13], v81, s67, v[148:149]
	s_waitcnt lgkmcnt(0)
	global_store_dwordx4 v[236:237], v[232:235], off
	v_pk_mul_f32 v[76:77], v[76:77], v[80:81] op_sel_hi:[1,0]
	v_pk_mul_f32 v[78:79], v[78:79], v[80:81] op_sel_hi:[1,0]
	v_pk_mul_f32 v[74:75], v[74:75], v[80:81] op_sel_hi:[1,0]
	v_pk_mul_f32 v[72:73], v[72:73], v[80:81] op_sel_hi:[1,0]
	v_pk_mul_f32 v[70:71], v[70:71], v[80:81] op_sel_hi:[1,0]
	v_pk_mul_f32 v[68:69], v[68:69], v[80:81] op_sel_hi:[1,0]
	v_mul_f32_e32 v81, 0xbfb8aa3b, v76
	v_exp_f32_e32 v81, v81
	v_mul_f32_e32 v84, 0xbfb8aa3b, v77
	v_exp_f32_e32 v86, v84
	v_lshl_add_u64 v[82:83], v[82:83], 0, v[150:151]
	v_pk_mul_f32 v[84:85], v[66:67], v[80:81] op_sel_hi:[1,0]
	v_add_f32_e32 v66, 1.0, v81
	v_rcp_f32_e32 v81, v66
	v_add_f32_e32 v66, 1.0, v86
	v_rcp_f32_e32 v86, v66
	v_pk_mul_f32 v[66:67], v[64:65], v[80:81] op_sel_hi:[1,0]
	v_mul_f32_e32 v64, v76, v81
	v_mul_f32_e32 v64, v68, v64
	v_mul_f32_e32 v68, 0xbfb8aa3b, v78
	v_mul_f32_e32 v76, 0xbfb8aa3b, v79
	v_exp_f32_e32 v68, v68
	v_exp_f32_e32 v76, v76
	v_mul_f32_e32 v65, v77, v86
	v_mul_f32_e32 v65, v69, v65
	v_add_f32_e32 v68, 1.0, v68
	v_add_f32_e32 v69, 1.0, v76
	v_rcp_f32_e32 v68, v68
	v_rcp_f32_e32 v69, v69
	v_cvt_pk_bf16_f32 v64, v64, v65
	v_mul_f32_e32 v65, v78, v68
	v_mul_f32_e32 v68, v79, v69
	v_mul_f32_e32 v69, 0xbfb8aa3b, v72
	v_mul_f32_e32 v65, v70, v65
	v_exp_f32_e32 v69, v69
	v_mul_f32_e32 v70, 0xbfb8aa3b, v73
	v_exp_f32_e32 v70, v70
	v_mul_f32_e32 v68, v71, v68
	v_add_f32_e32 v69, 1.0, v69
	v_rcp_f32_e32 v69, v69
	v_add_f32_e32 v70, 1.0, v70
	v_rcp_f32_e32 v70, v70
	v_cvt_pk_bf16_f32 v65, v65, v68
	v_mul_f32_e32 v68, v72, v69
	v_mul_f32_e32 v69, 0xbfb8aa3b, v74
	v_mul_f32_e32 v66, v66, v68
	v_mul_f32_e32 v68, v73, v70
	v_exp_f32_e32 v69, v69
	v_mul_f32_e32 v70, 0xbfb8aa3b, v75
	v_exp_f32_e32 v70, v70
	v_mul_f32_e32 v67, v67, v68
	v_add_f32_e32 v68, 1.0, v69
	v_rcp_f32_e32 v68, v68
	v_add_f32_e32 v69, 1.0, v70
	v_rcp_f32_e32 v69, v69
	v_cvt_pk_bf16_f32 v66, v66, v67
	v_mul_f32_e32 v67, v74, v68
	v_mul_f32_e32 v67, v84, v67
	v_mul_f32_e32 v68, v75, v69
	v_mul_f32_e32 v68, v85, v68
	v_cvt_pk_bf16_f32 v67, v67, v68
	ds_write_b128 v230, v[64:67]
	ds_read_b128 v[232:235], v231
	v_mov_b32_e32 v236, v82
	v_mov_b32_e32 v237, v83
	ds_read_b32 v64, v160 offset:512
	s_nop 0
	v_add_u32_e32 v65, 0x80, v159
	v_mad_i64_i32 v[66:67], s[12:13], v65, s67, v[148:149]
	s_waitcnt lgkmcnt(0)
	global_store_dwordx4 v[236:237], v[232:235], off
	v_pk_mul_f32 v[60:61], v[60:61], v[64:65] op_sel_hi:[1,0]
	v_pk_mul_f32 v[62:63], v[62:63], v[64:65] op_sel_hi:[1,0]
	v_pk_mul_f32 v[58:59], v[58:59], v[64:65] op_sel_hi:[1,0]
	v_pk_mul_f32 v[56:57], v[56:57], v[64:65] op_sel_hi:[1,0]
	v_pk_mul_f32 v[54:55], v[54:55], v[64:65] op_sel_hi:[1,0]
	v_pk_mul_f32 v[52:53], v[52:53], v[64:65] op_sel_hi:[1,0]
	v_mul_f32_e32 v65, 0xbfb8aa3b, v60
	v_exp_f32_e32 v65, v65
	v_mul_f32_e32 v68, 0xbfb8aa3b, v61
	v_exp_f32_e32 v70, v68
	v_lshl_add_u64 v[66:67], v[66:67], 0, v[150:151]
	v_pk_mul_f32 v[68:69], v[50:51], v[64:65] op_sel_hi:[1,0]
	v_add_f32_e32 v50, 1.0, v65
	v_rcp_f32_e32 v65, v50
	v_add_f32_e32 v50, 1.0, v70
	v_rcp_f32_e32 v70, v50
	v_pk_mul_f32 v[50:51], v[48:49], v[64:65] op_sel_hi:[1,0]
	v_mul_f32_e32 v48, v60, v65
	v_mul_f32_e32 v48, v52, v48
	v_mul_f32_e32 v52, 0xbfb8aa3b, v62
	v_mul_f32_e32 v60, 0xbfb8aa3b, v63
	v_exp_f32_e32 v52, v52
	v_exp_f32_e32 v60, v60
	v_mul_f32_e32 v49, v61, v70
	v_mul_f32_e32 v49, v53, v49
	v_add_f32_e32 v52, 1.0, v52
	v_add_f32_e32 v53, 1.0, v60
	v_rcp_f32_e32 v52, v52
	v_rcp_f32_e32 v53, v53
	v_cvt_pk_bf16_f32 v48, v48, v49
	v_mul_f32_e32 v49, v62, v52
	v_mul_f32_e32 v52, v63, v53
	v_mul_f32_e32 v53, 0xbfb8aa3b, v56
	v_mul_f32_e32 v49, v54, v49
	v_exp_f32_e32 v53, v53
	v_mul_f32_e32 v54, 0xbfb8aa3b, v57
	v_exp_f32_e32 v54, v54
	v_mul_f32_e32 v52, v55, v52
	v_add_f32_e32 v53, 1.0, v53
	v_rcp_f32_e32 v53, v53
	v_add_f32_e32 v54, 1.0, v54
	v_rcp_f32_e32 v54, v54
	v_cvt_pk_bf16_f32 v49, v49, v52
	v_mul_f32_e32 v52, v56, v53
	v_mul_f32_e32 v53, 0xbfb8aa3b, v58
	v_mul_f32_e32 v50, v50, v52
	v_mul_f32_e32 v52, v57, v54
	v_exp_f32_e32 v53, v53
	v_mul_f32_e32 v54, 0xbfb8aa3b, v59
	v_exp_f32_e32 v54, v54
	v_mul_f32_e32 v51, v51, v52
	v_add_f32_e32 v52, 1.0, v53
	v_rcp_f32_e32 v52, v52
	v_add_f32_e32 v53, 1.0, v54
	v_rcp_f32_e32 v53, v53
	v_cvt_pk_bf16_f32 v50, v50, v51
	v_mul_f32_e32 v51, v58, v52
	v_mul_f32_e32 v51, v68, v51
	v_mul_f32_e32 v52, v59, v53
	v_mul_f32_e32 v52, v69, v52
	v_cvt_pk_bf16_f32 v51, v51, v52
	ds_write_b128 v230, v[48:51]
	ds_read_b128 v[232:235], v231
	v_mov_b32_e32 v236, v66
	v_mov_b32_e32 v237, v67
	ds_read_b32 v48, v160 offset:576
	s_nop 0
	v_add_u32_e32 v49, 0x90, v159
	v_mad_i64_i32 v[50:51], s[12:13], v49, s67, v[148:149]
	s_waitcnt lgkmcnt(0)
	global_store_dwordx4 v[236:237], v[232:235], off
	v_pk_mul_f32 v[44:45], v[44:45], v[48:49] op_sel_hi:[1,0]
	v_pk_mul_f32 v[46:47], v[46:47], v[48:49] op_sel_hi:[1,0]
	v_pk_mul_f32 v[42:43], v[42:43], v[48:49] op_sel_hi:[1,0]
	v_pk_mul_f32 v[40:41], v[40:41], v[48:49] op_sel_hi:[1,0]
	v_pk_mul_f32 v[38:39], v[38:39], v[48:49] op_sel_hi:[1,0]
	v_pk_mul_f32 v[36:37], v[36:37], v[48:49] op_sel_hi:[1,0]
	v_mul_f32_e32 v49, 0xbfb8aa3b, v44
	v_exp_f32_e32 v49, v49
	v_mul_f32_e32 v52, 0xbfb8aa3b, v45
	v_exp_f32_e32 v54, v52
	v_lshl_add_u64 v[50:51], v[50:51], 0, v[150:151]
	v_pk_mul_f32 v[52:53], v[34:35], v[48:49] op_sel_hi:[1,0]
	v_add_f32_e32 v34, 1.0, v49
	v_rcp_f32_e32 v49, v34
	v_add_f32_e32 v34, 1.0, v54
	v_rcp_f32_e32 v54, v34
	v_pk_mul_f32 v[34:35], v[32:33], v[48:49] op_sel_hi:[1,0]
	v_mul_f32_e32 v32, v44, v49
	v_mul_f32_e32 v32, v36, v32
	v_mul_f32_e32 v36, 0xbfb8aa3b, v46
	v_mul_f32_e32 v44, 0xbfb8aa3b, v47
	v_exp_f32_e32 v36, v36
	v_exp_f32_e32 v44, v44
	v_mul_f32_e32 v33, v45, v54
	v_mul_f32_e32 v33, v37, v33
	v_add_f32_e32 v36, 1.0, v36
	v_add_f32_e32 v37, 1.0, v44
	v_rcp_f32_e32 v36, v36
	v_rcp_f32_e32 v37, v37
	v_cvt_pk_bf16_f32 v32, v32, v33
	v_mul_f32_e32 v33, v46, v36
	v_mul_f32_e32 v36, v47, v37
	v_mul_f32_e32 v37, 0xbfb8aa3b, v40
	v_mul_f32_e32 v33, v38, v33
	v_exp_f32_e32 v37, v37
	v_mul_f32_e32 v38, 0xbfb8aa3b, v41
	v_exp_f32_e32 v38, v38
	v_mul_f32_e32 v36, v39, v36
	v_add_f32_e32 v37, 1.0, v37
	v_rcp_f32_e32 v37, v37
	v_add_f32_e32 v38, 1.0, v38
	v_rcp_f32_e32 v38, v38
	v_cvt_pk_bf16_f32 v33, v33, v36
	v_mul_f32_e32 v36, v40, v37
	v_mul_f32_e32 v37, 0xbfb8aa3b, v42
	v_mul_f32_e32 v34, v34, v36
	v_mul_f32_e32 v36, v41, v38
	v_exp_f32_e32 v37, v37
	v_mul_f32_e32 v38, 0xbfb8aa3b, v43
	v_exp_f32_e32 v38, v38
	v_mul_f32_e32 v35, v35, v36
	v_add_f32_e32 v36, 1.0, v37
	v_rcp_f32_e32 v36, v36
	v_add_f32_e32 v37, 1.0, v38
	v_rcp_f32_e32 v37, v37
	v_cvt_pk_bf16_f32 v34, v34, v35
	v_mul_f32_e32 v35, v42, v36
	v_mul_f32_e32 v35, v52, v35
	v_mul_f32_e32 v36, v43, v37
	v_mul_f32_e32 v36, v53, v36
	v_cvt_pk_bf16_f32 v35, v35, v36
	ds_write_b128 v230, v[32:35]
	ds_read_b128 v[232:235], v231
	v_mov_b32_e32 v236, v50
	v_mov_b32_e32 v237, v51
	ds_read_b32 v32, v160 offset:640
	s_nop 0
	v_add_u32_e32 v33, 0xa0, v159
	v_mad_i64_i32 v[34:35], s[12:13], v33, s67, v[148:149]
	s_waitcnt lgkmcnt(0)
	global_store_dwordx4 v[236:237], v[232:235], off
	v_pk_mul_f32 v[28:29], v[28:29], v[32:33] op_sel_hi:[1,0]
	v_pk_mul_f32 v[30:31], v[30:31], v[32:33] op_sel_hi:[1,0]
	v_pk_mul_f32 v[26:27], v[26:27], v[32:33] op_sel_hi:[1,0]
	v_pk_mul_f32 v[24:25], v[24:25], v[32:33] op_sel_hi:[1,0]
	v_pk_mul_f32 v[22:23], v[22:23], v[32:33] op_sel_hi:[1,0]
	v_pk_mul_f32 v[20:21], v[20:21], v[32:33] op_sel_hi:[1,0]
	v_mul_f32_e32 v33, 0xbfb8aa3b, v28
	v_exp_f32_e32 v33, v33
	v_mul_f32_e32 v36, 0xbfb8aa3b, v29
	v_exp_f32_e32 v38, v36
	v_lshl_add_u64 v[34:35], v[34:35], 0, v[150:151]
	v_pk_mul_f32 v[36:37], v[18:19], v[32:33] op_sel_hi:[1,0]
	v_add_f32_e32 v18, 1.0, v33
	v_rcp_f32_e32 v33, v18
	v_add_f32_e32 v18, 1.0, v38
	v_rcp_f32_e32 v38, v18
	v_pk_mul_f32 v[18:19], v[16:17], v[32:33] op_sel_hi:[1,0]
	v_mul_f32_e32 v16, v28, v33
	v_mul_f32_e32 v16, v20, v16
	v_mul_f32_e32 v20, 0xbfb8aa3b, v30
	v_mul_f32_e32 v28, 0xbfb8aa3b, v31
	v_exp_f32_e32 v20, v20
	v_exp_f32_e32 v28, v28
	v_mul_f32_e32 v17, v29, v38
	v_mul_f32_e32 v17, v21, v17
	v_add_f32_e32 v20, 1.0, v20
	v_add_f32_e32 v21, 1.0, v28
	v_rcp_f32_e32 v20, v20
	v_rcp_f32_e32 v21, v21
	v_cvt_pk_bf16_f32 v16, v16, v17
	v_mul_f32_e32 v17, v30, v20
	v_mul_f32_e32 v20, v31, v21
	v_mul_f32_e32 v21, 0xbfb8aa3b, v24
	v_mul_f32_e32 v17, v22, v17
	v_exp_f32_e32 v21, v21
	v_mul_f32_e32 v22, 0xbfb8aa3b, v25
	v_exp_f32_e32 v22, v22
	v_mul_f32_e32 v20, v23, v20
	v_add_f32_e32 v21, 1.0, v21
	v_rcp_f32_e32 v21, v21
	v_add_f32_e32 v22, 1.0, v22
	v_rcp_f32_e32 v22, v22
	v_cvt_pk_bf16_f32 v17, v17, v20
	v_mul_f32_e32 v20, v24, v21
	v_mul_f32_e32 v21, 0xbfb8aa3b, v26
	v_mul_f32_e32 v18, v18, v20
	v_mul_f32_e32 v20, v25, v22
	v_exp_f32_e32 v21, v21
	v_mul_f32_e32 v22, 0xbfb8aa3b, v27
	v_exp_f32_e32 v22, v22
	v_mul_f32_e32 v19, v19, v20
	v_add_f32_e32 v20, 1.0, v21
	v_rcp_f32_e32 v20, v20
	v_add_f32_e32 v21, 1.0, v22
	v_rcp_f32_e32 v21, v21
	v_cvt_pk_bf16_f32 v18, v18, v19
	v_mul_f32_e32 v19, v26, v20
	v_mul_f32_e32 v19, v36, v19
	v_mul_f32_e32 v20, v27, v21
	v_mul_f32_e32 v20, v37, v20
	v_cvt_pk_bf16_f32 v19, v19, v20
	ds_write_b128 v230, v[16:19]
	ds_read_b128 v[232:235], v231
	v_mov_b32_e32 v236, v34
	v_mov_b32_e32 v237, v35
	ds_read_b32 v16, v160 offset:704
	s_nop 0
	v_add_u32_e32 v17, 0xb0, v159
	v_mad_i64_i32 v[18:19], s[12:13], v17, s67, v[148:149]
	s_waitcnt lgkmcnt(0)
	global_store_dwordx4 v[236:237], v[232:235], off
	v_pk_mul_f32 v[12:13], v[12:13], v[16:17] op_sel_hi:[1,0]
	v_pk_mul_f32 v[14:15], v[14:15], v[16:17] op_sel_hi:[1,0]
	v_pk_mul_f32 v[10:11], v[10:11], v[16:17] op_sel_hi:[1,0]
	v_pk_mul_f32 v[8:9], v[8:9], v[16:17] op_sel_hi:[1,0]
	v_pk_mul_f32 v[6:7], v[6:7], v[16:17] op_sel_hi:[1,0]
	v_pk_mul_f32 v[4:5], v[4:5], v[16:17] op_sel_hi:[1,0]
	v_mul_f32_e32 v17, 0xbfb8aa3b, v12
	v_exp_f32_e32 v17, v17
	v_mul_f32_e32 v20, 0xbfb8aa3b, v13
	v_exp_f32_e32 v22, v20
	v_lshl_add_u64 v[18:19], v[18:19], 0, v[150:151]
	v_pk_mul_f32 v[20:21], v[2:3], v[16:17] op_sel_hi:[1,0]
	v_add_f32_e32 v2, 1.0, v17
	v_rcp_f32_e32 v17, v2
	v_add_f32_e32 v2, 1.0, v22
	v_rcp_f32_e32 v22, v2
	v_pk_mul_f32 v[2:3], v[0:1], v[16:17] op_sel_hi:[1,0]
	v_mul_f32_e32 v0, v12, v17
	v_mul_f32_e32 v0, v4, v0
	v_mul_f32_e32 v4, 0xbfb8aa3b, v14
	v_mul_f32_e32 v12, 0xbfb8aa3b, v15
	v_exp_f32_e32 v4, v4
	v_exp_f32_e32 v12, v12
	v_mul_f32_e32 v1, v13, v22
	v_mul_f32_e32 v1, v5, v1
	v_add_f32_e32 v4, 1.0, v4
	v_add_f32_e32 v5, 1.0, v12
	v_rcp_f32_e32 v4, v4
	v_rcp_f32_e32 v5, v5
	v_cvt_pk_bf16_f32 v0, v0, v1
	v_mul_f32_e32 v1, v14, v4
	v_mul_f32_e32 v4, v15, v5
	v_mul_f32_e32 v5, 0xbfb8aa3b, v8
	v_mul_f32_e32 v1, v6, v1
	v_exp_f32_e32 v5, v5
	v_mul_f32_e32 v6, 0xbfb8aa3b, v9
	v_exp_f32_e32 v6, v6
	v_mul_f32_e32 v4, v7, v4
	v_add_f32_e32 v5, 1.0, v5
	v_rcp_f32_e32 v5, v5
	v_add_f32_e32 v6, 1.0, v6
	v_rcp_f32_e32 v6, v6
	v_cvt_pk_bf16_f32 v1, v1, v4
	v_mul_f32_e32 v4, v8, v5
	v_mul_f32_e32 v5, 0xbfb8aa3b, v10
	v_mul_f32_e32 v2, v2, v4
	v_mul_f32_e32 v4, v9, v6
	v_exp_f32_e32 v5, v5
	v_mul_f32_e32 v6, 0xbfb8aa3b, v11
	v_exp_f32_e32 v6, v6
	v_mul_f32_e32 v3, v3, v4
	v_add_f32_e32 v4, 1.0, v5
	v_rcp_f32_e32 v4, v4
	v_add_f32_e32 v5, 1.0, v6
	v_rcp_f32_e32 v5, v5
	v_cvt_pk_bf16_f32 v2, v2, v3
	v_mul_f32_e32 v3, v10, v4
	v_mul_f32_e32 v3, v20, v3
	v_mul_f32_e32 v4, v11, v5
	v_mul_f32_e32 v4, v21, v4
	v_cvt_pk_bf16_f32 v3, v3, v4
	ds_write_b128 v230, v[0:3]
	ds_read_b128 v[232:235], v231
	v_mov_b32_e32 v236, v18
	v_mov_b32_e32 v237, v19
	s_waitcnt lgkmcnt(0)
	global_store_dwordx4 v[236:237], v[232:235], off
	s_cbranch_vccnz .LBB0_472
	s_andn2_b64 vcc, exec, s[0:1]
	s_cbranch_vccnz .LBB0_471
	s_nop 0
	s_branch .LBB0_471

.LBB0_1053:
	s_lshl_b32 s6, s6, 5
	s_and_b32 s22, s6, 0x60
	s_mov_b64 s[6:7], 0x80
	s_add_i32 m0, s31, 0x18000
	v_lshl_add_u64 v[6:7], v[6:7], 0, s[6:7]
	s_lshl_b32 s11, s10, 13
	s_lshl_b32 s23, s22, 7
	s_waitcnt vmcnt(2)
	s_barrier
	global_load_lds_dwordx4 v[6:7], off
	v_lshl_add_u64 v[4:5], v[4:5], 0, s[6:7]
	s_add_i32 m0, s31, 0x1a000
	s_add_i32 s55, s31, 0x8000
	s_add_i32 s56, s31, 0xa000
	global_load_lds_dwordx4 v[4:5], off
	v_lshl_add_u64 v[0:1], v[0:1], 0, s[6:7]
	s_mov_b32 m0, s55
	s_add_u32 s8, s38, 0x40080
	global_load_lds_dwordx4 v[0:1], off
	v_lshl_add_u64 v[0:1], v[2:3], 0, s[6:7]
	s_mov_b32 m0, s56
	s_addc_u32 s9, s39, 0
	global_load_lds_dwordx4 v[0:1], off
	s_add_i32 m0, s31, 0x1c000
	v_lshl_add_u64 v[0:1], s[8:9], 0, v[136:137]
	global_load_lds_dwordx4 v[0:1], off
	v_lshl_add_u64 v[0:1], s[8:9], 0, v[132:133]
	s_add_i32 m0, s31, 0x1e000
	s_sext_i32_i16 s13, s4
	global_load_lds_dwordx4 v[0:1], off
	v_and_b32_e32 v0, 15, v128
	v_lshlrev_b32_e32 v1, 1, v12
	v_lshl_or_b32 v131, s10, 6, v0
	v_lshl_or_b32 v2, v0, 6, v1
	v_lshlrev_b32_e32 v0, 2, v0
	v_and_b32_e32 v3, 32, v0
	v_bitop3_b32 v2, v2, s11, v3 bitop3:0xde
	v_lshlrev_b32_e32 v3, 6, v128
	s_movk_i32 s4, 0x3c0
	s_cmpk_lt_u32 s5, 0x100
	v_and_or_b32 v1, v3, s4, v1
	s_cselect_b64 s[8:9], -1, 0
	s_lshl_b32 s4, s10, 8
	s_add_i32 s4, s4, 0
	s_add_i32 s4, s4, 0x20000
	v_and_b32_e32 v3, 32, v8
	v_add_u32_e32 v153, s4, v0
	v_lshlrev_b32_e32 v0, 8, v128
	v_bitop3_b32 v152, s23, v1, v3 bitop3:0xf6
	v_and_b32_e32 v0, 0x38000, v0
	v_lshlrev_b32_e32 v1, 11, v13
	v_or3_b32 v0, v10, v0, v1
	v_add_u32_e32 v140, v0, v11
	v_lshlrev_b32_e32 v0, 4, v9
	s_waitcnt vmcnt(6)
	v_and_b32_e32 v0, 0x78000, v0
	v_or3_b32 v0, v10, v0, v1
	s_add_i32 s57, 0, 0x10000
	s_add_i32 s58, 0, 0x14000
	v_mbcnt_lo_u32_b32 v233, -1, 0
	v_mbcnt_hi_u32_b32 v233, -1, v233
	v_lshrrev_b32_e32 v230, 2, v233
	v_and_b32_e32 v131, 0xffffffc0, v131
	v_or_b32_e32 v131, v131, v230
	v_lshrrev_b32_e32 v231, 3, v233
	v_xor_b32_e32 v231, v231, v233
	v_and_b32_e32 v231, 3, v231
	v_lshlrev_b32_e32 v231, 3, v231
	v_or_b32_e32 v154, s22, v231
	v_mov_b32_e32 v235, 0x23000
	v_lshl_add_u32 v235, s91, 10, v235
	v_lshl_add_u32 v231, v233, 4, v235
	v_and_b32_e32 v230, 15, v233
	v_lshrrev_b32_e32 v232, 1, v230
	v_lshrrev_b32_e32 v234, 4, v233
	v_xor_b32_e32 v232, v232, v234
	v_and_b32_e32 v232, 3, v232
	v_lshlrev_b32_e32 v232, 4, v232
	v_lshl_add_u32 v230, v230, 6, v232
	v_add_u32_e32 v230, v235, v230
	v_mov_b32_e32 v141, v137
	v_add_u32_e32 v142, v0, v11
	v_mov_b32_e32 v143, v137
	v_mov_b64_e32 v[144:145], 0xb00
	v_mov_b64_e32 v[146:147], 0xaff
	v_add_u32_e32 v155, s57, v152
	v_add_u32_e32 v157, s58, v152
	v_add_u32_e32 v158, 0, v2
	s_movk_i32 s59, 0x1600
	s_mov_b32 s62, 0
	s_barrier
	s_branch .LBB0_1056

.LBB0_1062:
	v_lshl_add_u32 v160, s12, 10, v153
	ds_read_b32 v162, v160
	v_lshl_or_b32 v150, s13, 7, v154
	v_lshl_add_u32 v159, s30, 8, v131
	v_ashrrev_i32_e32 v151, 31, v150
	v_mov_b64_e32 v[148:149], s[16:17]
	s_waitcnt lgkmcnt(0)
	v_pk_mul_f32 v[124:125], v[124:125], v[162:163] op_sel_hi:[1,0]
	v_pk_mul_f32 v[126:127], v[126:127], v[162:163] op_sel_hi:[1,0]
	v_pk_mul_f32 v[122:123], v[122:123], v[162:163] op_sel_hi:[1,0]
	v_pk_mul_f32 v[120:121], v[120:121], v[162:163] op_sel_hi:[1,0]
	v_pk_mul_f32 v[118:119], v[118:119], v[162:163] op_sel_hi:[1,0]
	v_pk_mul_f32 v[116:117], v[116:117], v[162:163] op_sel_hi:[1,0]
	v_mul_f32_e32 v161, 0xbfb8aa3b, v124
	v_mul_f32_e32 v163, 0xbfb8aa3b, v125
	v_exp_f32_e32 v161, v161
	v_exp_f32_e32 v163, v163
	v_mad_i64_i32 v[164:165], s[12:13], v159, s59, v[148:149]
	v_lshlrev_b64 v[150:151], 1, v[150:151]
	v_pk_mul_f32 v[166:167], v[114:115], v[162:163] op_sel_hi:[1,0]
	v_add_f32_e32 v114, 1.0, v161
	v_rcp_f32_e32 v161, v114
	v_add_f32_e32 v114, 1.0, v163
	v_rcp_f32_e32 v163, v114
	v_lshl_add_u64 v[164:165], v[164:165], 0, v[150:151]
	s_andn2_b64 vcc, exec, s[4:5]
	s_mov_b64 s[4:5], -1
	v_pk_mul_f32 v[114:115], v[112:113], v[162:163] op_sel_hi:[1,0]
	v_mul_f32_e32 v112, v124, v161
	v_mul_f32_e32 v112, v116, v112
	v_mul_f32_e32 v116, 0xbfb8aa3b, v126
	v_mul_f32_e32 v124, 0xbfb8aa3b, v127
	v_exp_f32_e32 v116, v116
	v_exp_f32_e32 v124, v124
	v_mul_f32_e32 v113, v125, v163
	v_mul_f32_e32 v113, v117, v113
	v_add_f32_e32 v116, 1.0, v116
	v_add_f32_e32 v117, 1.0, v124
	v_rcp_f32_e32 v116, v116
	v_rcp_f32_e32 v117, v117
	v_cvt_pk_bf16_f32 v112, v112, v113
	v_mul_f32_e32 v113, v126, v116
	v_mul_f32_e32 v116, v127, v117
	v_mul_f32_e32 v117, 0xbfb8aa3b, v120
	v_mul_f32_e32 v113, v118, v113
	v_exp_f32_e32 v117, v117
	v_mul_f32_e32 v118, 0xbfb8aa3b, v121
	v_exp_f32_e32 v118, v118
	v_mul_f32_e32 v116, v119, v116
	v_add_f32_e32 v117, 1.0, v117
	v_rcp_f32_e32 v117, v117
	v_add_f32_e32 v118, 1.0, v118
	v_rcp_f32_e32 v118, v118
	v_cvt_pk_bf16_f32 v113, v113, v116
	v_mul_f32_e32 v116, v120, v117
	v_mul_f32_e32 v117, 0xbfb8aa3b, v122
	v_mul_f32_e32 v114, v114, v116
	v_mul_f32_e32 v116, v121, v118
	v_exp_f32_e32 v117, v117
	v_mul_f32_e32 v118, 0xbfb8aa3b, v123
	v_exp_f32_e32 v118, v118
	v_mul_f32_e32 v115, v115, v116
	v_add_f32_e32 v116, 1.0, v117
	v_rcp_f32_e32 v116, v116
	v_add_f32_e32 v117, 1.0, v118
	v_rcp_f32_e32 v117, v117
	v_cvt_pk_bf16_f32 v114, v114, v115
	v_mul_f32_e32 v115, v122, v116
	v_mul_f32_e32 v115, v166, v115
	v_mul_f32_e32 v116, v123, v117
	v_mul_f32_e32 v116, v167, v116
	v_cvt_pk_bf16_f32 v115, v115, v116
	ds_write_b128 v230, v[112:115]
	ds_read_b128 v[232:235], v231
	v_mov_b32_e32 v236, v164
	v_mov_b32_e32 v237, v165
	ds_read_b32 v112, v160 offset:64
	s_nop 0
	v_or_b32_e32 v113, 16, v159
	v_mad_i64_i32 v[114:115], s[12:13], v113, s59, v[148:149]
	s_waitcnt lgkmcnt(0)
	global_store_dwordx4 v[236:237], v[232:235], off
	v_pk_mul_f32 v[108:109], v[108:109], v[112:113] op_sel_hi:[1,0]
	v_pk_mul_f32 v[110:111], v[110:111], v[112:113] op_sel_hi:[1,0]
	v_pk_mul_f32 v[106:107], v[106:107], v[112:113] op_sel_hi:[1,0]
	v_pk_mul_f32 v[104:105], v[104:105], v[112:113] op_sel_hi:[1,0]
	v_pk_mul_f32 v[102:103], v[102:103], v[112:113] op_sel_hi:[1,0]
	v_pk_mul_f32 v[100:101], v[100:101], v[112:113] op_sel_hi:[1,0]
	v_mul_f32_e32 v113, 0xbfb8aa3b, v108
	v_exp_f32_e32 v113, v113
	v_mul_f32_e32 v116, 0xbfb8aa3b, v109
	v_exp_f32_e32 v118, v116
	v_lshl_add_u64 v[114:115], v[114:115], 0, v[150:151]
	v_pk_mul_f32 v[116:117], v[98:99], v[112:113] op_sel_hi:[1,0]
	v_add_f32_e32 v98, 1.0, v113
	v_rcp_f32_e32 v113, v98
	v_add_f32_e32 v98, 1.0, v118
	v_rcp_f32_e32 v118, v98
	v_pk_mul_f32 v[98:99], v[96:97], v[112:113] op_sel_hi:[1,0]
	v_mul_f32_e32 v96, v108, v113
	v_mul_f32_e32 v96, v100, v96
	v_mul_f32_e32 v100, 0xbfb8aa3b, v110
	v_mul_f32_e32 v108, 0xbfb8aa3b, v111
	v_exp_f32_e32 v100, v100
	v_exp_f32_e32 v108, v108
	v_mul_f32_e32 v97, v109, v118
	v_mul_f32_e32 v97, v101, v97
	v_add_f32_e32 v100, 1.0, v100
	v_add_f32_e32 v101, 1.0, v108
	v_rcp_f32_e32 v100, v100
	v_rcp_f32_e32 v101, v101
	v_cvt_pk_bf16_f32 v96, v96, v97
	v_mul_f32_e32 v97, v110, v100
	v_mul_f32_e32 v100, v111, v101
	v_mul_f32_e32 v101, 0xbfb8aa3b, v104
	v_mul_f32_e32 v97, v102, v97
	v_exp_f32_e32 v101, v101
	v_mul_f32_e32 v102, 0xbfb8aa3b, v105
	v_exp_f32_e32 v102, v102
	v_mul_f32_e32 v100, v103, v100
	v_add_f32_e32 v101, 1.0, v101
	v_rcp_f32_e32 v101, v101
	v_add_f32_e32 v102, 1.0, v102
	v_rcp_f32_e32 v102, v102
	v_cvt_pk_bf16_f32 v97, v97, v100
	v_mul_f32_e32 v100, v104, v101
	v_mul_f32_e32 v101, 0xbfb8aa3b, v106
	v_mul_f32_e32 v98, v98, v100
	v_mul_f32_e32 v100, v105, v102
	v_exp_f32_e32 v101, v101
	v_mul_f32_e32 v102, 0xbfb8aa3b, v107
	v_exp_f32_e32 v102, v102
	v_mul_f32_e32 v99, v99, v100
	v_add_f32_e32 v100, 1.0, v101
	v_rcp_f32_e32 v100, v100
	v_add_f32_e32 v101, 1.0, v102
	v_rcp_f32_e32 v101, v101
	v_cvt_pk_bf16_f32 v98, v98, v99
	v_mul_f32_e32 v99, v106, v100
	v_mul_f32_e32 v99, v116, v99
	v_mul_f32_e32 v100, v107, v101
	v_mul_f32_e32 v100, v117, v100
	v_cvt_pk_bf16_f32 v99, v99, v100
	ds_write_b128 v230, v[96:99]
	ds_read_b128 v[232:235], v231
	v_mov_b32_e32 v236, v114
	v_mov_b32_e32 v237, v115
	ds_read_b32 v96, v160 offset:128
	s_nop 0
	v_or_b32_e32 v97, 32, v159
	v_mad_i64_i32 v[98:99], s[12:13], v97, s59, v[148:149]
	s_waitcnt lgkmcnt(0)
	global_store_dwordx4 v[236:237], v[232:235], off
	v_pk_mul_f32 v[92:93], v[92:93], v[96:97] op_sel_hi:[1,0]
	v_pk_mul_f32 v[94:95], v[94:95], v[96:97] op_sel_hi:[1,0]
	v_pk_mul_f32 v[90:91], v[90:91], v[96:97] op_sel_hi:[1,0]
	v_pk_mul_f32 v[88:89], v[88:89], v[96:97] op_sel_hi:[1,0]
	v_pk_mul_f32 v[86:87], v[86:87], v[96:97] op_sel_hi:[1,0]
	v_pk_mul_f32 v[84:85], v[84:85], v[96:97] op_sel_hi:[1,0]
	v_mul_f32_e32 v97, 0xbfb8aa3b, v92
	v_exp_f32_e32 v97, v97
	v_mul_f32_e32 v100, 0xbfb8aa3b, v93
	v_exp_f32_e32 v102, v100
	v_lshl_add_u64 v[98:99], v[98:99], 0, v[150:151]
	v_pk_mul_f32 v[100:101], v[82:83], v[96:97] op_sel_hi:[1,0]
	v_add_f32_e32 v82, 1.0, v97
	v_rcp_f32_e32 v97, v82
	v_add_f32_e32 v82, 1.0, v102
	v_rcp_f32_e32 v102, v82
	v_pk_mul_f32 v[82:83], v[80:81], v[96:97] op_sel_hi:[1,0]
	v_mul_f32_e32 v80, v92, v97
	v_mul_f32_e32 v80, v84, v80
	v_mul_f32_e32 v84, 0xbfb8aa3b, v94
	v_mul_f32_e32 v92, 0xbfb8aa3b, v95
	v_exp_f32_e32 v84, v84
	v_exp_f32_e32 v92, v92
	v_mul_f32_e32 v81, v93, v102
	v_mul_f32_e32 v81, v85, v81
	v_add_f32_e32 v84, 1.0, v84
	v_add_f32_e32 v85, 1.0, v92
	v_rcp_f32_e32 v84, v84
	v_rcp_f32_e32 v85, v85
	v_cvt_pk_bf16_f32 v80, v80, v81
	v_mul_f32_e32 v81, v94, v84
	v_mul_f32_e32 v84, v95, v85
	v_mul_f32_e32 v85, 0xbfb8aa3b, v88
	v_mul_f32_e32 v81, v86, v81
	v_exp_f32_e32 v85, v85
	v_mul_f32_e32 v86, 0xbfb8aa3b, v89
	v_exp_f32_e32 v86, v86
	v_mul_f32_e32 v84, v87, v84
	v_add_f32_e32 v85, 1.0, v85
	v_rcp_f32_e32 v85, v85
	v_add_f32_e32 v86, 1.0, v86
	v_rcp_f32_e32 v86, v86
	v_cvt_pk_bf16_f32 v81, v81, v84
	v_mul_f32_e32 v84, v88, v85
	v_mul_f32_e32 v85, 0xbfb8aa3b, v90
	v_mul_f32_e32 v82, v82, v84
	v_mul_f32_e32 v84, v89, v86
	v_exp_f32_e32 v85, v85
	v_mul_f32_e32 v86, 0xbfb8aa3b, v91
	v_exp_f32_e32 v86, v86
	v_mul_f32_e32 v83, v83, v84
	v_add_f32_e32 v84, 1.0, v85
	v_rcp_f32_e32 v84, v84
	v_add_f32_e32 v85, 1.0, v86
	v_rcp_f32_e32 v85, v85
	v_cvt_pk_bf16_f32 v82, v82, v83
	v_mul_f32_e32 v83, v90, v84
	v_mul_f32_e32 v83, v100, v83
	v_mul_f32_e32 v84, v91, v85
	v_mul_f32_e32 v84, v101, v84
	v_cvt_pk_bf16_f32 v83, v83, v84
	ds_write_b128 v230, v[80:83]
	ds_read_b128 v[232:235], v231
	v_mov_b32_e32 v236, v98
	v_mov_b32_e32 v237, v99
	ds_read_b32 v80, v160 offset:192
	s_nop 0
	v_or_b32_e32 v81, 48, v159
	v_mad_i64_i32 v[82:83], s[12:13], v81, s59, v[148:149]
	s_waitcnt lgkmcnt(0)
	global_store_dwordx4 v[236:237], v[232:235], off
	v_pk_mul_f32 v[76:77], v[76:77], v[80:81] op_sel_hi:[1,0]
	v_pk_mul_f32 v[78:79], v[78:79], v[80:81] op_sel_hi:[1,0]
	v_pk_mul_f32 v[74:75], v[74:75], v[80:81] op_sel_hi:[1,0]
	v_pk_mul_f32 v[72:73], v[72:73], v[80:81] op_sel_hi:[1,0]
	v_pk_mul_f32 v[70:71], v[70:71], v[80:81] op_sel_hi:[1,0]
	v_pk_mul_f32 v[68:69], v[68:69], v[80:81] op_sel_hi:[1,0]
	v_mul_f32_e32 v81, 0xbfb8aa3b, v76
	v_exp_f32_e32 v81, v81
	v_mul_f32_e32 v84, 0xbfb8aa3b, v77
	v_exp_f32_e32 v86, v84
	v_lshl_add_u64 v[82:83], v[82:83], 0, v[150:151]
	v_pk_mul_f32 v[84:85], v[66:67], v[80:81] op_sel_hi:[1,0]
	v_add_f32_e32 v66, 1.0, v81
	v_rcp_f32_e32 v81, v66
	v_add_f32_e32 v66, 1.0, v86
	v_rcp_f32_e32 v86, v66
	v_pk_mul_f32 v[66:67], v[64:65], v[80:81] op_sel_hi:[1,0]
	v_mul_f32_e32 v64, v76, v81
	v_mul_f32_e32 v64, v68, v64
	v_mul_f32_e32 v68, 0xbfb8aa3b, v78
	v_mul_f32_e32 v76, 0xbfb8aa3b, v79
	v_exp_f32_e32 v68, v68
	v_exp_f32_e32 v76, v76
	v_mul_f32_e32 v65, v77, v86
	v_mul_f32_e32 v65, v69, v65
	v_add_f32_e32 v68, 1.0, v68
	v_add_f32_e32 v69, 1.0, v76
	v_rcp_f32_e32 v68, v68
	v_rcp_f32_e32 v69, v69
	v_cvt_pk_bf16_f32 v64, v64, v65
	v_mul_f32_e32 v65, v78, v68
	v_mul_f32_e32 v68, v79, v69
	v_mul_f32_e32 v69, 0xbfb8aa3b, v72
	v_mul_f32_e32 v65, v70, v65
	v_exp_f32_e32 v69, v69
	v_mul_f32_e32 v70, 0xbfb8aa3b, v73
	v_exp_f32_e32 v70, v70
	v_mul_f32_e32 v68, v71, v68
	v_add_f32_e32 v69, 1.0, v69
	v_rcp_f32_e32 v69, v69
	v_add_f32_e32 v70, 1.0, v70
	v_rcp_f32_e32 v70, v70
	v_cvt_pk_bf16_f32 v65, v65, v68
	v_mul_f32_e32 v68, v72, v69
	v_mul_f32_e32 v69, 0xbfb8aa3b, v74
	v_mul_f32_e32 v66, v66, v68
	v_mul_f32_e32 v68, v73, v70
	v_exp_f32_e32 v69, v69
	v_mul_f32_e32 v70, 0xbfb8aa3b, v75
	v_exp_f32_e32 v70, v70
	v_mul_f32_e32 v67, v67, v68
	v_add_f32_e32 v68, 1.0, v69
	v_rcp_f32_e32 v68, v68
	v_add_f32_e32 v69, 1.0, v70
	v_rcp_f32_e32 v69, v69
	v_cvt_pk_bf16_f32 v66, v66, v67
	v_mul_f32_e32 v67, v74, v68
	v_mul_f32_e32 v67, v84, v67
	v_mul_f32_e32 v68, v75, v69
	v_mul_f32_e32 v68, v85, v68
	v_cvt_pk_bf16_f32 v67, v67, v68
	ds_write_b128 v230, v[64:67]
	ds_read_b128 v[232:235], v231
	v_mov_b32_e32 v236, v82
	v_mov_b32_e32 v237, v83
	ds_read_b32 v64, v160 offset:512
	s_nop 0
	v_add_u32_e32 v65, 0x80, v159
	v_mad_i64_i32 v[66:67], s[12:13], v65, s59, v[148:149]
	s_waitcnt lgkmcnt(0)
	global_store_dwordx4 v[236:237], v[232:235], off
	v_pk_mul_f32 v[60:61], v[60:61], v[64:65] op_sel_hi:[1,0]
	v_pk_mul_f32 v[62:63], v[62:63], v[64:65] op_sel_hi:[1,0]
	v_pk_mul_f32 v[58:59], v[58:59], v[64:65] op_sel_hi:[1,0]
	v_pk_mul_f32 v[56:57], v[56:57], v[64:65] op_sel_hi:[1,0]
	v_pk_mul_f32 v[54:55], v[54:55], v[64:65] op_sel_hi:[1,0]
	v_pk_mul_f32 v[52:53], v[52:53], v[64:65] op_sel_hi:[1,0]
	v_mul_f32_e32 v65, 0xbfb8aa3b, v60
	v_exp_f32_e32 v65, v65
	v_mul_f32_e32 v68, 0xbfb8aa3b, v61
	v_exp_f32_e32 v70, v68
	v_lshl_add_u64 v[66:67], v[66:67], 0, v[150:151]
	v_pk_mul_f32 v[68:69], v[50:51], v[64:65] op_sel_hi:[1,0]
	v_add_f32_e32 v50, 1.0, v65
	v_rcp_f32_e32 v65, v50
	v_add_f32_e32 v50, 1.0, v70
	v_rcp_f32_e32 v70, v50
	v_pk_mul_f32 v[50:51], v[48:49], v[64:65] op_sel_hi:[1,0]
	v_mul_f32_e32 v48, v60, v65
	v_mul_f32_e32 v48, v52, v48
	v_mul_f32_e32 v52, 0xbfb8aa3b, v62
	v_mul_f32_e32 v60, 0xbfb8aa3b, v63
	v_exp_f32_e32 v52, v52
	v_exp_f32_e32 v60, v60
	v_mul_f32_e32 v49, v61, v70
	v_mul_f32_e32 v49, v53, v49
	v_add_f32_e32 v52, 1.0, v52
	v_add_f32_e32 v53, 1.0, v60
	v_rcp_f32_e32 v52, v52
	v_rcp_f32_e32 v53, v53
	v_cvt_pk_bf16_f32 v48, v48, v49
	v_mul_f32_e32 v49, v62, v52
	v_mul_f32_e32 v52, v63, v53
	v_mul_f32_e32 v53, 0xbfb8aa3b, v56
	v_mul_f32_e32 v49, v54, v49
	v_exp_f32_e32 v53, v53
	v_mul_f32_e32 v54, 0xbfb8aa3b, v57
	v_exp_f32_e32 v54, v54
	v_mul_f32_e32 v52, v55, v52
	v_add_f32_e32 v53, 1.0, v53
	v_rcp_f32_e32 v53, v53
	v_add_f32_e32 v54, 1.0, v54
	v_rcp_f32_e32 v54, v54
	v_cvt_pk_bf16_f32 v49, v49, v52
	v_mul_f32_e32 v52, v56, v53
	v_mul_f32_e32 v53, 0xbfb8aa3b, v58
	v_mul_f32_e32 v50, v50, v52
	v_mul_f32_e32 v52, v57, v54
	v_exp_f32_e32 v53, v53
	v_mul_f32_e32 v54, 0xbfb8aa3b, v59
	v_exp_f32_e32 v54, v54
	v_mul_f32_e32 v51, v51, v52
	v_add_f32_e32 v52, 1.0, v53
	v_rcp_f32_e32 v52, v52
	v_add_f32_e32 v53, 1.0, v54
	v_rcp_f32_e32 v53, v53
	v_cvt_pk_bf16_f32 v50, v50, v51
	v_mul_f32_e32 v51, v58, v52
	v_mul_f32_e32 v51, v68, v51
	v_mul_f32_e32 v52, v59, v53
	v_mul_f32_e32 v52, v69, v52
	v_cvt_pk_bf16_f32 v51, v51, v52
	ds_write_b128 v230, v[48:51]
	ds_read_b128 v[232:235], v231
	v_mov_b32_e32 v236, v66
	v_mov_b32_e32 v237, v67
	ds_read_b32 v48, v160 offset:576
	s_nop 0
	v_add_u32_e32 v49, 0x90, v159
	v_mad_i64_i32 v[50:51], s[12:13], v49, s59, v[148:149]
	s_waitcnt lgkmcnt(0)
	global_store_dwordx4 v[236:237], v[232:235], off
	v_pk_mul_f32 v[44:45], v[44:45], v[48:49] op_sel_hi:[1,0]
	v_pk_mul_f32 v[46:47], v[46:47], v[48:49] op_sel_hi:[1,0]
	v_pk_mul_f32 v[42:43], v[42:43], v[48:49] op_sel_hi:[1,0]
	v_pk_mul_f32 v[40:41], v[40:41], v[48:49] op_sel_hi:[1,0]
	v_pk_mul_f32 v[38:39], v[38:39], v[48:49] op_sel_hi:[1,0]
	v_pk_mul_f32 v[36:37], v[36:37], v[48:49] op_sel_hi:[1,0]
	v_mul_f32_e32 v49, 0xbfb8aa3b, v44
	v_exp_f32_e32 v49, v49
	v_mul_f32_e32 v52, 0xbfb8aa3b, v45
	v_exp_f32_e32 v54, v52
	v_lshl_add_u64 v[50:51], v[50:51], 0, v[150:151]
	v_pk_mul_f32 v[52:53], v[34:35], v[48:49] op_sel_hi:[1,0]
	v_add_f32_e32 v34, 1.0, v49
	v_rcp_f32_e32 v49, v34
	v_add_f32_e32 v34, 1.0, v54
	v_rcp_f32_e32 v54, v34
	v_pk_mul_f32 v[34:35], v[32:33], v[48:49] op_sel_hi:[1,0]
	v_mul_f32_e32 v32, v44, v49
	v_mul_f32_e32 v32, v36, v32
	v_mul_f32_e32 v36, 0xbfb8aa3b, v46
	v_mul_f32_e32 v44, 0xbfb8aa3b, v47
	v_exp_f32_e32 v36, v36
	v_exp_f32_e32 v44, v44
	v_mul_f32_e32 v33, v45, v54
	v_mul_f32_e32 v33, v37, v33
	v_add_f32_e32 v36, 1.0, v36
	v_add_f32_e32 v37, 1.0, v44
	v_rcp_f32_e32 v36, v36
	v_rcp_f32_e32 v37, v37
	v_cvt_pk_bf16_f32 v32, v32, v33
	v_mul_f32_e32 v33, v46, v36
	v_mul_f32_e32 v36, v47, v37
	v_mul_f32_e32 v37, 0xbfb8aa3b, v40
	v_mul_f32_e32 v33, v38, v33
	v_exp_f32_e32 v37, v37
	v_mul_f32_e32 v38, 0xbfb8aa3b, v41
	v_exp_f32_e32 v38, v38
	v_mul_f32_e32 v36, v39, v36
	v_add_f32_e32 v37, 1.0, v37
	v_rcp_f32_e32 v37, v37
	v_add_f32_e32 v38, 1.0, v38
	v_rcp_f32_e32 v38, v38
	v_cvt_pk_bf16_f32 v33, v33, v36
	v_mul_f32_e32 v36, v40, v37
	v_mul_f32_e32 v37, 0xbfb8aa3b, v42
	v_mul_f32_e32 v34, v34, v36
	v_mul_f32_e32 v36, v41, v38
	v_exp_f32_e32 v37, v37
	v_mul_f32_e32 v38, 0xbfb8aa3b, v43
	v_exp_f32_e32 v38, v38
	v_mul_f32_e32 v35, v35, v36
	v_add_f32_e32 v36, 1.0, v37
	v_rcp_f32_e32 v36, v36
	v_add_f32_e32 v37, 1.0, v38
	v_rcp_f32_e32 v37, v37
	v_cvt_pk_bf16_f32 v34, v34, v35
	v_mul_f32_e32 v35, v42, v36
	v_mul_f32_e32 v35, v52, v35
	v_mul_f32_e32 v36, v43, v37
	v_mul_f32_e32 v36, v53, v36
	v_cvt_pk_bf16_f32 v35, v35, v36
	ds_write_b128 v230, v[32:35]
	ds_read_b128 v[232:235], v231
	v_mov_b32_e32 v236, v50
	v_mov_b32_e32 v237, v51
	ds_read_b32 v32, v160 offset:640
	s_nop 0
	v_add_u32_e32 v33, 0xa0, v159
	v_mad_i64_i32 v[34:35], s[12:13], v33, s59, v[148:149]
	s_waitcnt lgkmcnt(0)
	global_store_dwordx4 v[236:237], v[232:235], off
	v_pk_mul_f32 v[28:29], v[28:29], v[32:33] op_sel_hi:[1,0]
	v_pk_mul_f32 v[30:31], v[30:31], v[32:33] op_sel_hi:[1,0]
	v_pk_mul_f32 v[26:27], v[26:27], v[32:33] op_sel_hi:[1,0]
	v_pk_mul_f32 v[24:25], v[24:25], v[32:33] op_sel_hi:[1,0]
	v_pk_mul_f32 v[22:23], v[22:23], v[32:33] op_sel_hi:[1,0]
	v_pk_mul_f32 v[20:21], v[20:21], v[32:33] op_sel_hi:[1,0]
	v_mul_f32_e32 v33, 0xbfb8aa3b, v28
	v_exp_f32_e32 v33, v33
	v_mul_f32_e32 v36, 0xbfb8aa3b, v29
	v_exp_f32_e32 v38, v36
	v_lshl_add_u64 v[34:35], v[34:35], 0, v[150:151]
	v_pk_mul_f32 v[36:37], v[18:19], v[32:33] op_sel_hi:[1,0]
	v_add_f32_e32 v18, 1.0, v33
	v_rcp_f32_e32 v33, v18
	v_add_f32_e32 v18, 1.0, v38
	v_rcp_f32_e32 v38, v18
	v_pk_mul_f32 v[18:19], v[16:17], v[32:33] op_sel_hi:[1,0]
	v_mul_f32_e32 v16, v28, v33
	v_mul_f32_e32 v16, v20, v16
	v_mul_f32_e32 v20, 0xbfb8aa3b, v30
	v_mul_f32_e32 v28, 0xbfb8aa3b, v31
	v_exp_f32_e32 v20, v20
	v_exp_f32_e32 v28, v28
	v_mul_f32_e32 v17, v29, v38
	v_mul_f32_e32 v17, v21, v17
	v_add_f32_e32 v20, 1.0, v20
	v_add_f32_e32 v21, 1.0, v28
	v_rcp_f32_e32 v20, v20
	v_rcp_f32_e32 v21, v21
	v_cvt_pk_bf16_f32 v16, v16, v17
	v_mul_f32_e32 v17, v30, v20
	v_mul_f32_e32 v20, v31, v21
	v_mul_f32_e32 v21, 0xbfb8aa3b, v24
	v_mul_f32_e32 v17, v22, v17
	v_exp_f32_e32 v21, v21
	v_mul_f32_e32 v22, 0xbfb8aa3b, v25
	v_exp_f32_e32 v22, v22
	v_mul_f32_e32 v20, v23, v20
	v_add_f32_e32 v21, 1.0, v21
	v_rcp_f32_e32 v21, v21
	v_add_f32_e32 v22, 1.0, v22
	v_rcp_f32_e32 v22, v22
	v_cvt_pk_bf16_f32 v17, v17, v20
	v_mul_f32_e32 v20, v24, v21
	v_mul_f32_e32 v21, 0xbfb8aa3b, v26
	v_mul_f32_e32 v18, v18, v20
	v_mul_f32_e32 v20, v25, v22
	v_exp_f32_e32 v21, v21
	v_mul_f32_e32 v22, 0xbfb8aa3b, v27
	v_exp_f32_e32 v22, v22
	v_mul_f32_e32 v19, v19, v20
	v_add_f32_e32 v20, 1.0, v21
	v_rcp_f32_e32 v20, v20
	v_add_f32_e32 v21, 1.0, v22
	v_rcp_f32_e32 v21, v21
	v_cvt_pk_bf16_f32 v18, v18, v19
	v_mul_f32_e32 v19, v26, v20
	v_mul_f32_e32 v19, v36, v19
	v_mul_f32_e32 v20, v27, v21
	v_mul_f32_e32 v20, v37, v20
	v_cvt_pk_bf16_f32 v19, v19, v20
	ds_write_b128 v230, v[16:19]
	ds_read_b128 v[232:235], v231
	v_mov_b32_e32 v236, v34
	v_mov_b32_e32 v237, v35
	ds_read_b32 v16, v160 offset:704
	s_nop 0
	v_add_u32_e32 v17, 0xb0, v159
	v_mad_i64_i32 v[18:19], s[12:13], v17, s59, v[148:149]
	s_waitcnt lgkmcnt(0)
	global_store_dwordx4 v[236:237], v[232:235], off
	v_pk_mul_f32 v[12:13], v[12:13], v[16:17] op_sel_hi:[1,0]
	v_pk_mul_f32 v[14:15], v[14:15], v[16:17] op_sel_hi:[1,0]
	v_pk_mul_f32 v[10:11], v[10:11], v[16:17] op_sel_hi:[1,0]
	v_pk_mul_f32 v[8:9], v[8:9], v[16:17] op_sel_hi:[1,0]
	v_pk_mul_f32 v[6:7], v[6:7], v[16:17] op_sel_hi:[1,0]
	v_pk_mul_f32 v[4:5], v[4:5], v[16:17] op_sel_hi:[1,0]
	v_mul_f32_e32 v17, 0xbfb8aa3b, v12
	v_exp_f32_e32 v17, v17
	v_mul_f32_e32 v20, 0xbfb8aa3b, v13
	v_exp_f32_e32 v22, v20
	v_lshl_add_u64 v[18:19], v[18:19], 0, v[150:151]
	v_pk_mul_f32 v[20:21], v[2:3], v[16:17] op_sel_hi:[1,0]
	v_add_f32_e32 v2, 1.0, v17
	v_rcp_f32_e32 v17, v2
	v_add_f32_e32 v2, 1.0, v22
	v_rcp_f32_e32 v22, v2
	v_pk_mul_f32 v[2:3], v[0:1], v[16:17] op_sel_hi:[1,0]
	v_mul_f32_e32 v0, v12, v17
	v_mul_f32_e32 v0, v4, v0
	v_mul_f32_e32 v4, 0xbfb8aa3b, v14
	v_mul_f32_e32 v12, 0xbfb8aa3b, v15
	v_exp_f32_e32 v4, v4
	v_exp_f32_e32 v12, v12
	v_mul_f32_e32 v1, v13, v22
	v_mul_f32_e32 v1, v5, v1
	v_add_f32_e32 v4, 1.0, v4
	v_add_f32_e32 v5, 1.0, v12
	v_rcp_f32_e32 v4, v4
	v_rcp_f32_e32 v5, v5
	v_cvt_pk_bf16_f32 v0, v0, v1
	v_mul_f32_e32 v1, v14, v4
	v_mul_f32_e32 v4, v15, v5
	v_mul_f32_e32 v5, 0xbfb8aa3b, v8
	v_mul_f32_e32 v1, v6, v1
	v_exp_f32_e32 v5, v5
	v_mul_f32_e32 v6, 0xbfb8aa3b, v9
	v_exp_f32_e32 v6, v6
	v_mul_f32_e32 v4, v7, v4
	v_add_f32_e32 v5, 1.0, v5
	v_rcp_f32_e32 v5, v5
	v_add_f32_e32 v6, 1.0, v6
	v_rcp_f32_e32 v6, v6
	v_cvt_pk_bf16_f32 v1, v1, v4
	v_mul_f32_e32 v4, v8, v5
	v_mul_f32_e32 v5, 0xbfb8aa3b, v10
	v_mul_f32_e32 v2, v2, v4
	v_mul_f32_e32 v4, v9, v6
	v_exp_f32_e32 v5, v5
	v_mul_f32_e32 v6, 0xbfb8aa3b, v11
	v_exp_f32_e32 v6, v6
	v_mul_f32_e32 v3, v3, v4
	v_add_f32_e32 v4, 1.0, v5
	v_rcp_f32_e32 v4, v4
	v_add_f32_e32 v5, 1.0, v6
	v_rcp_f32_e32 v5, v5
	v_cvt_pk_bf16_f32 v2, v2, v3
	v_mul_f32_e32 v3, v10, v4
	v_mul_f32_e32 v3, v20, v3
	v_mul_f32_e32 v4, v11, v5
	v_mul_f32_e32 v4, v21, v4
	v_cvt_pk_bf16_f32 v3, v3, v4
	ds_write_b128 v230, v[0:3]
	ds_read_b128 v[232:235], v231
	v_mov_b32_e32 v236, v18
	v_mov_b32_e32 v237, v19
	s_waitcnt lgkmcnt(0)
	global_store_dwordx4 v[236:237], v[232:235], off
	s_cbranch_vccnz .LBB0_1055
	s_andn2_b64 vcc, exec, s[0:1]
	s_cbranch_vccnz .LBB0_1054
	s_nop 0
	s_branch .LBB0_1054

.LBB0_1641:
	s_lshl_b32 s6, s6, 5
	s_and_b32 s22, s6, 0x60
	s_mov_b64 s[6:7], 0x80
	s_add_i32 m0, s31, 0x18000
	v_lshl_add_u64 v[6:7], v[6:7], 0, s[6:7]
	s_lshl_b32 s11, s10, 13
	s_lshl_b32 s23, s22, 7
	s_waitcnt vmcnt(2)
	s_barrier
	global_load_lds_dwordx4 v[6:7], off
	v_lshl_add_u64 v[4:5], v[4:5], 0, s[6:7]
	s_add_i32 m0, s31, 0x1a000
	s_add_i32 s51, s31, 0x8000
	s_add_i32 s52, s31, 0xa000
	global_load_lds_dwordx4 v[4:5], off
	v_lshl_add_u64 v[0:1], v[0:1], 0, s[6:7]
	s_mov_b32 m0, s51
	s_add_u32 s8, s38, 0x40080
	global_load_lds_dwordx4 v[0:1], off
	v_lshl_add_u64 v[0:1], v[2:3], 0, s[6:7]
	s_mov_b32 m0, s52
	s_addc_u32 s9, s39, 0
	global_load_lds_dwordx4 v[0:1], off
	s_add_i32 m0, s31, 0x1c000
	v_lshl_add_u64 v[0:1], s[8:9], 0, v[134:135]
	global_load_lds_dwordx4 v[0:1], off
	v_lshl_add_u64 v[0:1], s[8:9], 0, v[130:131]
	s_add_i32 m0, s31, 0x1e000
	s_sext_i32_i16 s13, s4
	global_load_lds_dwordx4 v[0:1], off
	v_and_b32_e32 v0, 15, v128
	v_lshlrev_b32_e32 v1, 1, v12
	v_lshl_or_b32 v150, s10, 6, v0
	v_lshl_or_b32 v2, v0, 6, v1
	v_lshlrev_b32_e32 v0, 2, v0
	v_and_b32_e32 v3, 32, v0
	v_bitop3_b32 v2, v2, s11, v3 bitop3:0xde
	v_lshlrev_b32_e32 v3, 6, v128
	s_movk_i32 s4, 0x3c0
	s_cmpk_lt_u32 s5, 0x100
	v_and_or_b32 v1, v3, s4, v1
	s_cselect_b64 s[8:9], -1, 0
	s_lshl_b32 s4, s10, 8
	s_add_i32 s4, s4, 0
	s_add_i32 s4, s4, 0x20000
	v_and_b32_e32 v3, 32, v8
	v_add_u32_e32 v152, s4, v0
	v_lshlrev_b32_e32 v0, 8, v128
	v_bitop3_b32 v151, s23, v1, v3 bitop3:0xf6
	v_and_b32_e32 v0, 0x38000, v0
	v_lshlrev_b32_e32 v1, 11, v13
	v_or3_b32 v0, v10, v0, v1
	v_add_u32_e32 v138, v0, v11
	v_lshlrev_b32_e32 v0, 4, v9
	s_waitcnt vmcnt(6)
	v_and_b32_e32 v0, 0x78000, v0
	v_or3_b32 v0, v10, v0, v1
	s_add_i32 s53, 0, 0x10000
	s_add_i32 s54, 0, 0x14000
	v_mbcnt_lo_u32_b32 v233, -1, 0
	v_mbcnt_hi_u32_b32 v233, -1, v233
	v_lshrrev_b32_e32 v230, 2, v233
	v_and_b32_e32 v150, 0xffffffc0, v150
	v_or_b32_e32 v150, v150, v230
	v_lshrrev_b32_e32 v231, 3, v233
	v_xor_b32_e32 v231, v231, v233
	v_and_b32_e32 v231, 3, v231
	v_lshlrev_b32_e32 v231, 3, v231
	v_or_b32_e32 v153, s22, v231
	v_mov_b32_e32 v235, 0x23000
	v_lshl_add_u32 v235, s91, 10, v235
	v_lshl_add_u32 v231, v233, 4, v235
	v_and_b32_e32 v230, 15, v233
	v_lshrrev_b32_e32 v232, 1, v230
	v_lshrrev_b32_e32 v234, 4, v233
	v_xor_b32_e32 v232, v232, v234
	v_and_b32_e32 v232, 3, v232
	v_lshlrev_b32_e32 v232, 4, v232
	v_lshl_add_u32 v230, v230, 6, v232
	v_add_u32_e32 v230, v235, v230
	v_mov_b32_e32 v139, v135
	v_add_u32_e32 v140, v0, v11
	v_mov_b32_e32 v141, v135
	v_mov_b64_e32 v[142:143], 0xb00
	v_mov_b64_e32 v[144:145], 0xaff
	v_add_u32_e32 v154, s53, v151
	v_add_u32_e32 v155, s54, v151
	v_add_u32_e32 v157, 0, v2
	s_movk_i32 s55, 0x1600
	s_mov_b32 s56, 0
	s_barrier
	s_branch .LBB0_1644

.LBB0_1650:
	v_lshl_add_u32 v159, s12, 10, v152
	ds_read_b32 v160, v159
	v_lshl_or_b32 v148, s13, 7, v153
	v_lshl_add_u32 v158, s30, 8, v150
	v_ashrrev_i32_e32 v149, 31, v148
	v_mov_b64_e32 v[146:147], s[16:17]
	s_waitcnt lgkmcnt(0)
	v_pk_mul_f32 v[124:125], v[124:125], v[160:161] op_sel_hi:[1,0]
	v_pk_mul_f32 v[126:127], v[126:127], v[160:161] op_sel_hi:[1,0]
	v_pk_mul_f32 v[122:123], v[122:123], v[160:161] op_sel_hi:[1,0]
	v_pk_mul_f32 v[120:121], v[120:121], v[160:161] op_sel_hi:[1,0]
	v_pk_mul_f32 v[118:119], v[118:119], v[160:161] op_sel_hi:[1,0]
	v_pk_mul_f32 v[116:117], v[116:117], v[160:161] op_sel_hi:[1,0]
	v_mul_f32_e32 v161, 0xbfb8aa3b, v124
	v_exp_f32_e32 v161, v161
	v_mul_f32_e32 v164, 0xbfb8aa3b, v125
	v_exp_f32_e32 v166, v164
	v_mad_i64_i32 v[162:163], s[12:13], v158, s55, v[146:147]
	v_pk_mul_f32 v[164:165], v[114:115], v[160:161] op_sel_hi:[1,0]
	v_add_f32_e32 v114, 1.0, v161
	v_rcp_f32_e32 v161, v114
	v_add_f32_e32 v114, 1.0, v166
	v_rcp_f32_e32 v166, v114
	v_lshlrev_b64 v[148:149], 1, v[148:149]
	v_pk_mul_f32 v[114:115], v[112:113], v[160:161] op_sel_hi:[1,0]
	v_mul_f32_e32 v112, v124, v161
	v_mul_f32_e32 v112, v116, v112
	v_mul_f32_e32 v116, 0xbfb8aa3b, v126
	v_mul_f32_e32 v124, 0xbfb8aa3b, v127
	v_exp_f32_e32 v116, v116
	v_exp_f32_e32 v124, v124
	v_mul_f32_e32 v113, v125, v166
	v_mul_f32_e32 v113, v117, v113
	v_add_f32_e32 v116, 1.0, v116
	v_add_f32_e32 v117, 1.0, v124
	v_rcp_f32_e32 v116, v116
	v_rcp_f32_e32 v117, v117
	v_cvt_pk_bf16_f32 v112, v112, v113
	v_lshl_add_u64 v[162:163], v[162:163], 0, v[148:149]
	v_mul_f32_e32 v113, v126, v116
	v_mul_f32_e32 v116, v127, v117
	v_mul_f32_e32 v117, 0xbfb8aa3b, v120
	v_mul_f32_e32 v113, v118, v113
	v_exp_f32_e32 v117, v117
	v_mul_f32_e32 v118, 0xbfb8aa3b, v121
	v_exp_f32_e32 v118, v118
	v_mul_f32_e32 v116, v119, v116
	v_add_f32_e32 v117, 1.0, v117
	v_rcp_f32_e32 v117, v117
	v_add_f32_e32 v118, 1.0, v118
	v_rcp_f32_e32 v118, v118
	v_cvt_pk_bf16_f32 v113, v113, v116
	v_mul_f32_e32 v116, v120, v117
	v_mul_f32_e32 v117, 0xbfb8aa3b, v122
	v_mul_f32_e32 v114, v114, v116
	v_mul_f32_e32 v116, v121, v118
	v_exp_f32_e32 v117, v117
	v_mul_f32_e32 v118, 0xbfb8aa3b, v123
	v_exp_f32_e32 v118, v118
	v_mul_f32_e32 v115, v115, v116
	v_add_f32_e32 v116, 1.0, v117
	v_rcp_f32_e32 v116, v116
	v_add_f32_e32 v117, 1.0, v118
	v_rcp_f32_e32 v117, v117
	v_cvt_pk_bf16_f32 v114, v114, v115
	v_mul_f32_e32 v115, v122, v116
	v_mul_f32_e32 v115, v164, v115
	v_mul_f32_e32 v116, v123, v117
	v_mul_f32_e32 v116, v165, v116
	v_cvt_pk_bf16_f32 v115, v115, v116
	ds_write_b128 v230, v[112:115]
	ds_read_b128 v[232:235], v231
	v_mov_b32_e32 v236, v162
	v_mov_b32_e32 v237, v163
	ds_read_b32 v112, v159 offset:64
	s_andn2_b64 vcc, exec, s[4:5]
	v_or_b32_e32 v113, 16, v158
	v_mad_i64_i32 v[114:115], s[12:13], v113, s55, v[146:147]
	s_waitcnt lgkmcnt(0)
	global_store_dwordx4 v[236:237], v[232:235], off
	v_pk_mul_f32 v[108:109], v[108:109], v[112:113] op_sel_hi:[1,0]
	v_pk_mul_f32 v[110:111], v[110:111], v[112:113] op_sel_hi:[1,0]
	v_pk_mul_f32 v[106:107], v[106:107], v[112:113] op_sel_hi:[1,0]
	v_pk_mul_f32 v[104:105], v[104:105], v[112:113] op_sel_hi:[1,0]
	v_pk_mul_f32 v[102:103], v[102:103], v[112:113] op_sel_hi:[1,0]
	v_pk_mul_f32 v[100:101], v[100:101], v[112:113] op_sel_hi:[1,0]
	v_mul_f32_e32 v113, 0xbfb8aa3b, v108
	v_exp_f32_e32 v113, v113
	v_mul_f32_e32 v116, 0xbfb8aa3b, v109
	v_exp_f32_e32 v118, v116
	v_lshl_add_u64 v[114:115], v[114:115], 0, v[148:149]
	v_pk_mul_f32 v[116:117], v[98:99], v[112:113] op_sel_hi:[1,0]
	v_add_f32_e32 v98, 1.0, v113
	v_rcp_f32_e32 v113, v98
	v_add_f32_e32 v98, 1.0, v118
	v_rcp_f32_e32 v118, v98
	s_mov_b64 s[4:5], -1
	v_pk_mul_f32 v[98:99], v[96:97], v[112:113] op_sel_hi:[1,0]
	v_mul_f32_e32 v96, v108, v113
	v_mul_f32_e32 v96, v100, v96
	v_mul_f32_e32 v100, 0xbfb8aa3b, v110
	v_mul_f32_e32 v108, 0xbfb8aa3b, v111
	v_exp_f32_e32 v100, v100
	v_exp_f32_e32 v108, v108
	v_mul_f32_e32 v97, v109, v118
	v_mul_f32_e32 v97, v101, v97
	v_add_f32_e32 v100, 1.0, v100
	v_add_f32_e32 v101, 1.0, v108
	v_rcp_f32_e32 v100, v100
	v_rcp_f32_e32 v101, v101
	v_cvt_pk_bf16_f32 v96, v96, v97
	v_mul_f32_e32 v97, v110, v100
	v_mul_f32_e32 v100, v111, v101
	v_mul_f32_e32 v101, 0xbfb8aa3b, v104
	v_mul_f32_e32 v97, v102, v97
	v_exp_f32_e32 v101, v101
	v_mul_f32_e32 v102, 0xbfb8aa3b, v105
	v_exp_f32_e32 v102, v102
	v_mul_f32_e32 v100, v103, v100
	v_add_f32_e32 v101, 1.0, v101
	v_rcp_f32_e32 v101, v101
	v_add_f32_e32 v102, 1.0, v102
	v_rcp_f32_e32 v102, v102
	v_cvt_pk_bf16_f32 v97, v97, v100
	v_mul_f32_e32 v100, v104, v101
	v_mul_f32_e32 v101, 0xbfb8aa3b, v106
	v_mul_f32_e32 v98, v98, v100
	v_mul_f32_e32 v100, v105, v102
	v_exp_f32_e32 v101, v101
	v_mul_f32_e32 v102, 0xbfb8aa3b, v107
	v_exp_f32_e32 v102, v102
	v_mul_f32_e32 v99, v99, v100
	v_add_f32_e32 v100, 1.0, v101
	v_rcp_f32_e32 v100, v100
	v_add_f32_e32 v101, 1.0, v102
	v_rcp_f32_e32 v101, v101
	v_cvt_pk_bf16_f32 v98, v98, v99
	v_mul_f32_e32 v99, v106, v100
	v_mul_f32_e32 v99, v116, v99
	v_mul_f32_e32 v100, v107, v101
	v_mul_f32_e32 v100, v117, v100
	v_cvt_pk_bf16_f32 v99, v99, v100
	ds_write_b128 v230, v[96:99]
	ds_read_b128 v[232:235], v231
	v_mov_b32_e32 v236, v114
	v_mov_b32_e32 v237, v115
	ds_read_b32 v96, v159 offset:128
	s_nop 0
	v_or_b32_e32 v97, 32, v158
	v_mad_i64_i32 v[98:99], s[12:13], v97, s55, v[146:147]
	s_waitcnt lgkmcnt(0)
	global_store_dwordx4 v[236:237], v[232:235], off
	v_pk_mul_f32 v[92:93], v[92:93], v[96:97] op_sel_hi:[1,0]
	v_pk_mul_f32 v[94:95], v[94:95], v[96:97] op_sel_hi:[1,0]
	v_pk_mul_f32 v[90:91], v[90:91], v[96:97] op_sel_hi:[1,0]
	v_pk_mul_f32 v[88:89], v[88:89], v[96:97] op_sel_hi:[1,0]
	v_pk_mul_f32 v[86:87], v[86:87], v[96:97] op_sel_hi:[1,0]
	v_pk_mul_f32 v[84:85], v[84:85], v[96:97] op_sel_hi:[1,0]
	v_mul_f32_e32 v97, 0xbfb8aa3b, v92
	v_exp_f32_e32 v97, v97
	v_mul_f32_e32 v100, 0xbfb8aa3b, v93
	v_exp_f32_e32 v102, v100
	v_lshl_add_u64 v[98:99], v[98:99], 0, v[148:149]
	v_pk_mul_f32 v[100:101], v[82:83], v[96:97] op_sel_hi:[1,0]
	v_add_f32_e32 v82, 1.0, v97
	v_rcp_f32_e32 v97, v82
	v_add_f32_e32 v82, 1.0, v102
	v_rcp_f32_e32 v102, v82
	v_pk_mul_f32 v[82:83], v[80:81], v[96:97] op_sel_hi:[1,0]
	v_mul_f32_e32 v80, v92, v97
	v_mul_f32_e32 v80, v84, v80
	v_mul_f32_e32 v84, 0xbfb8aa3b, v94
	v_mul_f32_e32 v92, 0xbfb8aa3b, v95
	v_exp_f32_e32 v84, v84
	v_exp_f32_e32 v92, v92
	v_mul_f32_e32 v81, v93, v102
	v_mul_f32_e32 v81, v85, v81
	v_add_f32_e32 v84, 1.0, v84
	v_add_f32_e32 v85, 1.0, v92
	v_rcp_f32_e32 v84, v84
	v_rcp_f32_e32 v85, v85
	v_cvt_pk_bf16_f32 v80, v80, v81
	v_mul_f32_e32 v81, v94, v84
	v_mul_f32_e32 v84, v95, v85
	v_mul_f32_e32 v85, 0xbfb8aa3b, v88
	v_mul_f32_e32 v81, v86, v81
	v_exp_f32_e32 v85, v85
	v_mul_f32_e32 v86, 0xbfb8aa3b, v89
	v_exp_f32_e32 v86, v86
	v_mul_f32_e32 v84, v87, v84
	v_add_f32_e32 v85, 1.0, v85
	v_rcp_f32_e32 v85, v85
	v_add_f32_e32 v86, 1.0, v86
	v_rcp_f32_e32 v86, v86
	v_cvt_pk_bf16_f32 v81, v81, v84
	v_mul_f32_e32 v84, v88, v85
	v_mul_f32_e32 v85, 0xbfb8aa3b, v90
	v_mul_f32_e32 v82, v82, v84
	v_mul_f32_e32 v84, v89, v86
	v_exp_f32_e32 v85, v85
	v_mul_f32_e32 v86, 0xbfb8aa3b, v91
	v_exp_f32_e32 v86, v86
	v_mul_f32_e32 v83, v83, v84
	v_add_f32_e32 v84, 1.0, v85
	v_rcp_f32_e32 v84, v84
	v_add_f32_e32 v85, 1.0, v86
	v_rcp_f32_e32 v85, v85
	v_cvt_pk_bf16_f32 v82, v82, v83
	v_mul_f32_e32 v83, v90, v84
	v_mul_f32_e32 v83, v100, v83
	v_mul_f32_e32 v84, v91, v85
	v_mul_f32_e32 v84, v101, v84
	v_cvt_pk_bf16_f32 v83, v83, v84
	ds_write_b128 v230, v[80:83]
	ds_read_b128 v[232:235], v231
	v_mov_b32_e32 v236, v98
	v_mov_b32_e32 v237, v99
	ds_read_b32 v80, v159 offset:192
	s_nop 0
	v_or_b32_e32 v81, 48, v158
	v_mad_i64_i32 v[82:83], s[12:13], v81, s55, v[146:147]
	s_waitcnt lgkmcnt(0)
	global_store_dwordx4 v[236:237], v[232:235], off
	v_pk_mul_f32 v[76:77], v[76:77], v[80:81] op_sel_hi:[1,0]
	v_pk_mul_f32 v[78:79], v[78:79], v[80:81] op_sel_hi:[1,0]
	v_pk_mul_f32 v[74:75], v[74:75], v[80:81] op_sel_hi:[1,0]
	v_pk_mul_f32 v[72:73], v[72:73], v[80:81] op_sel_hi:[1,0]
	v_pk_mul_f32 v[70:71], v[70:71], v[80:81] op_sel_hi:[1,0]
	v_pk_mul_f32 v[68:69], v[68:69], v[80:81] op_sel_hi:[1,0]
	v_mul_f32_e32 v81, 0xbfb8aa3b, v76
	v_exp_f32_e32 v81, v81
	v_mul_f32_e32 v84, 0xbfb8aa3b, v77
	v_exp_f32_e32 v86, v84
	v_lshl_add_u64 v[82:83], v[82:83], 0, v[148:149]
	v_pk_mul_f32 v[84:85], v[66:67], v[80:81] op_sel_hi:[1,0]
	v_add_f32_e32 v66, 1.0, v81
	v_rcp_f32_e32 v81, v66
	v_add_f32_e32 v66, 1.0, v86
	v_rcp_f32_e32 v86, v66
	v_pk_mul_f32 v[66:67], v[64:65], v[80:81] op_sel_hi:[1,0]
	v_mul_f32_e32 v64, v76, v81
	v_mul_f32_e32 v64, v68, v64
	v_mul_f32_e32 v68, 0xbfb8aa3b, v78
	v_mul_f32_e32 v76, 0xbfb8aa3b, v79
	v_exp_f32_e32 v68, v68
	v_exp_f32_e32 v76, v76
	v_mul_f32_e32 v65, v77, v86
	v_mul_f32_e32 v65, v69, v65
	v_add_f32_e32 v68, 1.0, v68
	v_add_f32_e32 v69, 1.0, v76
	v_rcp_f32_e32 v68, v68
	v_rcp_f32_e32 v69, v69
	v_cvt_pk_bf16_f32 v64, v64, v65
	v_mul_f32_e32 v65, v78, v68
	v_mul_f32_e32 v68, v79, v69
	v_mul_f32_e32 v69, 0xbfb8aa3b, v72
	v_mul_f32_e32 v65, v70, v65
	v_exp_f32_e32 v69, v69
	v_mul_f32_e32 v70, 0xbfb8aa3b, v73
	v_exp_f32_e32 v70, v70
	v_mul_f32_e32 v68, v71, v68
	v_add_f32_e32 v69, 1.0, v69
	v_rcp_f32_e32 v69, v69
	v_add_f32_e32 v70, 1.0, v70
	v_rcp_f32_e32 v70, v70
	v_cvt_pk_bf16_f32 v65, v65, v68
	v_mul_f32_e32 v68, v72, v69
	v_mul_f32_e32 v69, 0xbfb8aa3b, v74
	v_mul_f32_e32 v66, v66, v68
	v_mul_f32_e32 v68, v73, v70
	v_exp_f32_e32 v69, v69
	v_mul_f32_e32 v70, 0xbfb8aa3b, v75
	v_exp_f32_e32 v70, v70
	v_mul_f32_e32 v67, v67, v68
	v_add_f32_e32 v68, 1.0, v69
	v_rcp_f32_e32 v68, v68
	v_add_f32_e32 v69, 1.0, v70
	v_rcp_f32_e32 v69, v69
	v_cvt_pk_bf16_f32 v66, v66, v67
	v_mul_f32_e32 v67, v74, v68
	v_mul_f32_e32 v67, v84, v67
	v_mul_f32_e32 v68, v75, v69
	v_mul_f32_e32 v68, v85, v68
	v_cvt_pk_bf16_f32 v67, v67, v68
	ds_write_b128 v230, v[64:67]
	ds_read_b128 v[232:235], v231
	v_mov_b32_e32 v236, v82
	v_mov_b32_e32 v237, v83
	ds_read_b32 v64, v159 offset:512
	s_nop 0
	v_add_u32_e32 v65, 0x80, v158
	v_mad_i64_i32 v[66:67], s[12:13], v65, s55, v[146:147]
	s_waitcnt lgkmcnt(0)
	global_store_dwordx4 v[236:237], v[232:235], off
	v_pk_mul_f32 v[60:61], v[60:61], v[64:65] op_sel_hi:[1,0]
	v_pk_mul_f32 v[62:63], v[62:63], v[64:65] op_sel_hi:[1,0]
	v_pk_mul_f32 v[58:59], v[58:59], v[64:65] op_sel_hi:[1,0]
	v_pk_mul_f32 v[56:57], v[56:57], v[64:65] op_sel_hi:[1,0]
	v_pk_mul_f32 v[54:55], v[54:55], v[64:65] op_sel_hi:[1,0]
	v_pk_mul_f32 v[52:53], v[52:53], v[64:65] op_sel_hi:[1,0]
	v_mul_f32_e32 v65, 0xbfb8aa3b, v60
	v_exp_f32_e32 v65, v65
	v_mul_f32_e32 v68, 0xbfb8aa3b, v61
	v_exp_f32_e32 v70, v68
	v_lshl_add_u64 v[66:67], v[66:67], 0, v[148:149]
	v_pk_mul_f32 v[68:69], v[50:51], v[64:65] op_sel_hi:[1,0]
	v_add_f32_e32 v50, 1.0, v65
	v_rcp_f32_e32 v65, v50
	v_add_f32_e32 v50, 1.0, v70
	v_rcp_f32_e32 v70, v50
	v_pk_mul_f32 v[50:51], v[48:49], v[64:65] op_sel_hi:[1,0]
	v_mul_f32_e32 v48, v60, v65
	v_mul_f32_e32 v48, v52, v48
	v_mul_f32_e32 v52, 0xbfb8aa3b, v62
	v_mul_f32_e32 v60, 0xbfb8aa3b, v63
	v_exp_f32_e32 v52, v52
	v_exp_f32_e32 v60, v60
	v_mul_f32_e32 v49, v61, v70
	v_mul_f32_e32 v49, v53, v49
	v_add_f32_e32 v52, 1.0, v52
	v_add_f32_e32 v53, 1.0, v60
	v_rcp_f32_e32 v52, v52
	v_rcp_f32_e32 v53, v53
	v_cvt_pk_bf16_f32 v48, v48, v49
	v_mul_f32_e32 v49, v62, v52
	v_mul_f32_e32 v52, v63, v53
	v_mul_f32_e32 v53, 0xbfb8aa3b, v56
	v_mul_f32_e32 v49, v54, v49
	v_exp_f32_e32 v53, v53
	v_mul_f32_e32 v54, 0xbfb8aa3b, v57
	v_exp_f32_e32 v54, v54
	v_mul_f32_e32 v52, v55, v52
	v_add_f32_e32 v53, 1.0, v53
	v_rcp_f32_e32 v53, v53
	v_add_f32_e32 v54, 1.0, v54
	v_rcp_f32_e32 v54, v54
	v_cvt_pk_bf16_f32 v49, v49, v52
	v_mul_f32_e32 v52, v56, v53
	v_mul_f32_e32 v53, 0xbfb8aa3b, v58
	v_mul_f32_e32 v50, v50, v52
	v_mul_f32_e32 v52, v57, v54
	v_exp_f32_e32 v53, v53
	v_mul_f32_e32 v54, 0xbfb8aa3b, v59
	v_exp_f32_e32 v54, v54
	v_mul_f32_e32 v51, v51, v52
	v_add_f32_e32 v52, 1.0, v53
	v_rcp_f32_e32 v52, v52
	v_add_f32_e32 v53, 1.0, v54
	v_rcp_f32_e32 v53, v53
	v_cvt_pk_bf16_f32 v50, v50, v51
	v_mul_f32_e32 v51, v58, v52
	v_mul_f32_e32 v51, v68, v51
	v_mul_f32_e32 v52, v59, v53
	v_mul_f32_e32 v52, v69, v52
	v_cvt_pk_bf16_f32 v51, v51, v52
	ds_write_b128 v230, v[48:51]
	ds_read_b128 v[232:235], v231
	v_mov_b32_e32 v236, v66
	v_mov_b32_e32 v237, v67
	ds_read_b32 v48, v159 offset:576
	s_nop 0
	v_add_u32_e32 v49, 0x90, v158
	v_mad_i64_i32 v[50:51], s[12:13], v49, s55, v[146:147]
	s_waitcnt lgkmcnt(0)
	global_store_dwordx4 v[236:237], v[232:235], off
	v_pk_mul_f32 v[44:45], v[44:45], v[48:49] op_sel_hi:[1,0]
	v_pk_mul_f32 v[46:47], v[46:47], v[48:49] op_sel_hi:[1,0]
	v_pk_mul_f32 v[42:43], v[42:43], v[48:49] op_sel_hi:[1,0]
	v_pk_mul_f32 v[40:41], v[40:41], v[48:49] op_sel_hi:[1,0]
	v_pk_mul_f32 v[38:39], v[38:39], v[48:49] op_sel_hi:[1,0]
	v_pk_mul_f32 v[36:37], v[36:37], v[48:49] op_sel_hi:[1,0]
	v_mul_f32_e32 v49, 0xbfb8aa3b, v44
	v_exp_f32_e32 v49, v49
	v_mul_f32_e32 v52, 0xbfb8aa3b, v45
	v_exp_f32_e32 v54, v52
	v_lshl_add_u64 v[50:51], v[50:51], 0, v[148:149]
	v_pk_mul_f32 v[52:53], v[34:35], v[48:49] op_sel_hi:[1,0]
	v_add_f32_e32 v34, 1.0, v49
	v_rcp_f32_e32 v49, v34
	v_add_f32_e32 v34, 1.0, v54
	v_rcp_f32_e32 v54, v34
	v_pk_mul_f32 v[34:35], v[32:33], v[48:49] op_sel_hi:[1,0]
	v_mul_f32_e32 v32, v44, v49
	v_mul_f32_e32 v32, v36, v32
	v_mul_f32_e32 v36, 0xbfb8aa3b, v46
	v_mul_f32_e32 v44, 0xbfb8aa3b, v47
	v_exp_f32_e32 v36, v36
	v_exp_f32_e32 v44, v44
	v_mul_f32_e32 v33, v45, v54
	v_mul_f32_e32 v33, v37, v33
	v_add_f32_e32 v36, 1.0, v36
	v_add_f32_e32 v37, 1.0, v44
	v_rcp_f32_e32 v36, v36
	v_rcp_f32_e32 v37, v37
	v_cvt_pk_bf16_f32 v32, v32, v33
	v_mul_f32_e32 v33, v46, v36
	v_mul_f32_e32 v36, v47, v37
	v_mul_f32_e32 v37, 0xbfb8aa3b, v40
	v_mul_f32_e32 v33, v38, v33
	v_exp_f32_e32 v37, v37
	v_mul_f32_e32 v38, 0xbfb8aa3b, v41
	v_exp_f32_e32 v38, v38
	v_mul_f32_e32 v36, v39, v36
	v_add_f32_e32 v37, 1.0, v37
	v_rcp_f32_e32 v37, v37
	v_add_f32_e32 v38, 1.0, v38
	v_rcp_f32_e32 v38, v38
	v_cvt_pk_bf16_f32 v33, v33, v36
	v_mul_f32_e32 v36, v40, v37
	v_mul_f32_e32 v37, 0xbfb8aa3b, v42
	v_mul_f32_e32 v34, v34, v36
	v_mul_f32_e32 v36, v41, v38
	v_exp_f32_e32 v37, v37
	v_mul_f32_e32 v38, 0xbfb8aa3b, v43
	v_exp_f32_e32 v38, v38
	v_mul_f32_e32 v35, v35, v36
	v_add_f32_e32 v36, 1.0, v37
	v_rcp_f32_e32 v36, v36
	v_add_f32_e32 v37, 1.0, v38
	v_rcp_f32_e32 v37, v37
	v_cvt_pk_bf16_f32 v34, v34, v35
	v_mul_f32_e32 v35, v42, v36
	v_mul_f32_e32 v35, v52, v35
	v_mul_f32_e32 v36, v43, v37
	v_mul_f32_e32 v36, v53, v36
	v_cvt_pk_bf16_f32 v35, v35, v36
	ds_write_b128 v230, v[32:35]
	ds_read_b128 v[232:235], v231
	v_mov_b32_e32 v236, v50
	v_mov_b32_e32 v237, v51
	ds_read_b32 v32, v159 offset:640
	s_nop 0
	v_add_u32_e32 v33, 0xa0, v158
	v_mad_i64_i32 v[34:35], s[12:13], v33, s55, v[146:147]
	s_waitcnt lgkmcnt(0)
	global_store_dwordx4 v[236:237], v[232:235], off
	v_pk_mul_f32 v[28:29], v[28:29], v[32:33] op_sel_hi:[1,0]
	v_pk_mul_f32 v[30:31], v[30:31], v[32:33] op_sel_hi:[1,0]
	v_pk_mul_f32 v[26:27], v[26:27], v[32:33] op_sel_hi:[1,0]
	v_pk_mul_f32 v[24:25], v[24:25], v[32:33] op_sel_hi:[1,0]
	v_pk_mul_f32 v[22:23], v[22:23], v[32:33] op_sel_hi:[1,0]
	v_pk_mul_f32 v[20:21], v[20:21], v[32:33] op_sel_hi:[1,0]
	v_mul_f32_e32 v33, 0xbfb8aa3b, v28
	v_exp_f32_e32 v33, v33
	v_mul_f32_e32 v36, 0xbfb8aa3b, v29
	v_exp_f32_e32 v38, v36
	v_lshl_add_u64 v[34:35], v[34:35], 0, v[148:149]
	v_pk_mul_f32 v[36:37], v[18:19], v[32:33] op_sel_hi:[1,0]
	v_add_f32_e32 v18, 1.0, v33
	v_rcp_f32_e32 v33, v18
	v_add_f32_e32 v18, 1.0, v38
	v_rcp_f32_e32 v38, v18
	v_pk_mul_f32 v[18:19], v[16:17], v[32:33] op_sel_hi:[1,0]
	v_mul_f32_e32 v16, v28, v33
	v_mul_f32_e32 v16, v20, v16
	v_mul_f32_e32 v20, 0xbfb8aa3b, v30
	v_mul_f32_e32 v28, 0xbfb8aa3b, v31
	v_exp_f32_e32 v20, v20
	v_exp_f32_e32 v28, v28
	v_mul_f32_e32 v17, v29, v38
	v_mul_f32_e32 v17, v21, v17
	v_add_f32_e32 v20, 1.0, v20
	v_add_f32_e32 v21, 1.0, v28
	v_rcp_f32_e32 v20, v20
	v_rcp_f32_e32 v21, v21
	v_cvt_pk_bf16_f32 v16, v16, v17
	v_mul_f32_e32 v17, v30, v20
	v_mul_f32_e32 v20, v31, v21
	v_mul_f32_e32 v21, 0xbfb8aa3b, v24
	v_mul_f32_e32 v17, v22, v17
	v_exp_f32_e32 v21, v21
	v_mul_f32_e32 v22, 0xbfb8aa3b, v25
	v_exp_f32_e32 v22, v22
	v_mul_f32_e32 v20, v23, v20
	v_add_f32_e32 v21, 1.0, v21
	v_rcp_f32_e32 v21, v21
	v_add_f32_e32 v22, 1.0, v22
	v_rcp_f32_e32 v22, v22
	v_cvt_pk_bf16_f32 v17, v17, v20
	v_mul_f32_e32 v20, v24, v21
	v_mul_f32_e32 v21, 0xbfb8aa3b, v26
	v_mul_f32_e32 v18, v18, v20
	v_mul_f32_e32 v20, v25, v22
	v_exp_f32_e32 v21, v21
	v_mul_f32_e32 v22, 0xbfb8aa3b, v27
	v_exp_f32_e32 v22, v22
	v_mul_f32_e32 v19, v19, v20
	v_add_f32_e32 v20, 1.0, v21
	v_rcp_f32_e32 v20, v20
	v_add_f32_e32 v21, 1.0, v22
	v_rcp_f32_e32 v21, v21
	v_cvt_pk_bf16_f32 v18, v18, v19
	v_mul_f32_e32 v19, v26, v20
	v_mul_f32_e32 v19, v36, v19
	v_mul_f32_e32 v20, v27, v21
	v_mul_f32_e32 v20, v37, v20
	v_cvt_pk_bf16_f32 v19, v19, v20
	ds_write_b128 v230, v[16:19]
	ds_read_b128 v[232:235], v231
	v_mov_b32_e32 v236, v34
	v_mov_b32_e32 v237, v35
	ds_read_b32 v16, v159 offset:704
	s_nop 0
	v_add_u32_e32 v17, 0xb0, v158
	v_mad_i64_i32 v[18:19], s[12:13], v17, s55, v[146:147]
	s_waitcnt lgkmcnt(0)
	global_store_dwordx4 v[236:237], v[232:235], off
	v_pk_mul_f32 v[12:13], v[12:13], v[16:17] op_sel_hi:[1,0]
	v_pk_mul_f32 v[14:15], v[14:15], v[16:17] op_sel_hi:[1,0]
	v_pk_mul_f32 v[10:11], v[10:11], v[16:17] op_sel_hi:[1,0]
	v_pk_mul_f32 v[8:9], v[8:9], v[16:17] op_sel_hi:[1,0]
	v_pk_mul_f32 v[6:7], v[6:7], v[16:17] op_sel_hi:[1,0]
	v_pk_mul_f32 v[4:5], v[4:5], v[16:17] op_sel_hi:[1,0]
	v_mul_f32_e32 v17, 0xbfb8aa3b, v12
	v_exp_f32_e32 v17, v17
	v_mul_f32_e32 v20, 0xbfb8aa3b, v13
	v_exp_f32_e32 v22, v20
	v_lshl_add_u64 v[18:19], v[18:19], 0, v[148:149]
	v_pk_mul_f32 v[20:21], v[2:3], v[16:17] op_sel_hi:[1,0]
	v_add_f32_e32 v2, 1.0, v17
	v_rcp_f32_e32 v17, v2
	v_add_f32_e32 v2, 1.0, v22
	v_rcp_f32_e32 v22, v2
	v_pk_mul_f32 v[2:3], v[0:1], v[16:17] op_sel_hi:[1,0]
	v_mul_f32_e32 v0, v12, v17
	v_mul_f32_e32 v0, v4, v0
	v_mul_f32_e32 v4, 0xbfb8aa3b, v14
	v_mul_f32_e32 v12, 0xbfb8aa3b, v15
	v_exp_f32_e32 v4, v4
	v_exp_f32_e32 v12, v12
	v_mul_f32_e32 v1, v13, v22
	v_mul_f32_e32 v1, v5, v1
	v_add_f32_e32 v4, 1.0, v4
	v_add_f32_e32 v5, 1.0, v12
	v_rcp_f32_e32 v4, v4
	v_rcp_f32_e32 v5, v5
	v_cvt_pk_bf16_f32 v0, v0, v1
	v_mul_f32_e32 v1, v14, v4
	v_mul_f32_e32 v4, v15, v5
	v_mul_f32_e32 v5, 0xbfb8aa3b, v8
	v_mul_f32_e32 v1, v6, v1
	v_exp_f32_e32 v5, v5
	v_mul_f32_e32 v6, 0xbfb8aa3b, v9
	v_exp_f32_e32 v6, v6
	v_mul_f32_e32 v4, v7, v4
	v_add_f32_e32 v5, 1.0, v5
	v_rcp_f32_e32 v5, v5
	v_add_f32_e32 v6, 1.0, v6
	v_rcp_f32_e32 v6, v6
	v_cvt_pk_bf16_f32 v1, v1, v4
	v_mul_f32_e32 v4, v8, v5
	v_mul_f32_e32 v5, 0xbfb8aa3b, v10
	v_mul_f32_e32 v2, v2, v4
	v_mul_f32_e32 v4, v9, v6
	v_exp_f32_e32 v5, v5
	v_mul_f32_e32 v6, 0xbfb8aa3b, v11
	v_exp_f32_e32 v6, v6
	v_mul_f32_e32 v3, v3, v4
	v_add_f32_e32 v4, 1.0, v5
	v_rcp_f32_e32 v4, v4
	v_add_f32_e32 v5, 1.0, v6
	v_rcp_f32_e32 v5, v5
	v_cvt_pk_bf16_f32 v2, v2, v3
	v_mul_f32_e32 v3, v10, v4
	v_mul_f32_e32 v3, v20, v3
	v_mul_f32_e32 v4, v11, v5
	v_mul_f32_e32 v4, v21, v4
	v_cvt_pk_bf16_f32 v3, v3, v4
	ds_write_b128 v230, v[0:3]
	ds_read_b128 v[232:235], v231
	v_mov_b32_e32 v236, v18
	v_mov_b32_e32 v237, v19
	s_waitcnt lgkmcnt(0)
	global_store_dwordx4 v[236:237], v[232:235], off
	s_cbranch_vccnz .LBB0_1643
	s_andn2_b64 vcc, exec, s[0:1]
	s_cbranch_vccnz .LBB0_1642
	s_nop 0
	s_branch .LBB0_1642

.LBB0_2085:
	s_lshl_b32 s6, s6, 5
	s_and_b32 s18, s6, 0x60
	s_mov_b64 s[6:7], 0x80
	s_add_i32 m0, s25, 0x18000
	v_lshl_add_u64 v[6:7], v[6:7], 0, s[6:7]
	s_lshl_b32 s11, s10, 13
	s_lshl_b32 s19, s18, 7
	s_waitcnt vmcnt(2)
	s_barrier
	global_load_lds_dwordx4 v[6:7], off
	v_lshl_add_u64 v[4:5], v[4:5], 0, s[6:7]
	s_add_i32 m0, s25, 0x1a000
	s_add_i32 s45, s25, 0x8000
	s_add_i32 s46, s25, 0xa000
	global_load_lds_dwordx4 v[4:5], off
	v_lshl_add_u64 v[0:1], v[0:1], 0, s[6:7]
	s_mov_b32 m0, s45
	s_add_u32 s8, s28, 0x40080
	global_load_lds_dwordx4 v[0:1], off
	v_lshl_add_u64 v[0:1], v[2:3], 0, s[6:7]
	s_mov_b32 m0, s46
	s_addc_u32 s9, s29, 0
	global_load_lds_dwordx4 v[0:1], off
	s_add_i32 m0, s25, 0x1c000
	v_lshl_add_u64 v[0:1], s[8:9], 0, v[134:135]
	global_load_lds_dwordx4 v[0:1], off
	v_lshl_add_u64 v[0:1], s[8:9], 0, v[130:131]
	s_add_i32 m0, s25, 0x1e000
	s_sext_i32_i16 s13, s4
	global_load_lds_dwordx4 v[0:1], off
	v_and_b32_e32 v0, 15, v128
	v_lshlrev_b32_e32 v1, 1, v12
	v_lshl_or_b32 v129, s10, 6, v0
	v_lshl_or_b32 v2, v0, 6, v1
	v_lshlrev_b32_e32 v0, 2, v0
	v_and_b32_e32 v3, 32, v0
	v_bitop3_b32 v2, v2, s11, v3 bitop3:0xde
	v_lshlrev_b32_e32 v3, 6, v128
	s_movk_i32 s4, 0x3c0
	s_cmpk_lt_u32 s5, 0x100
	v_and_or_b32 v1, v3, s4, v1
	s_cselect_b64 s[8:9], -1, 0
	s_lshl_b32 s4, s10, 8
	s_add_i32 s4, s4, 0
	s_add_i32 s4, s4, 0x20000
	v_and_b32_e32 v3, 32, v8
	v_add_u32_e32 v151, s4, v0
	v_lshlrev_b32_e32 v0, 8, v128
	v_bitop3_b32 v150, s19, v1, v3 bitop3:0xf6
	v_and_b32_e32 v0, 0x38000, v0
	v_lshlrev_b32_e32 v1, 11, v13
	v_or3_b32 v0, v10, v0, v1
	v_add_u32_e32 v138, v0, v11
	v_lshlrev_b32_e32 v0, 4, v9
	s_waitcnt vmcnt(6)
	v_and_b32_e32 v0, 0x78000, v0
	v_or3_b32 v0, v10, v0, v1
	s_add_i32 s47, 0, 0x10000
	s_add_i32 s48, 0, 0x14000
	v_mbcnt_lo_u32_b32 v233, -1, 0
	v_mbcnt_hi_u32_b32 v233, -1, v233
	v_lshrrev_b32_e32 v230, 2, v233
	v_and_b32_e32 v129, 0xffffffc0, v129
	v_or_b32_e32 v129, v129, v230
	v_lshrrev_b32_e32 v231, 3, v233
	v_xor_b32_e32 v231, v231, v233
	v_and_b32_e32 v231, 3, v231
	v_lshlrev_b32_e32 v231, 3, v231
	v_or_b32_e32 v152, s18, v231
	v_mov_b32_e32 v235, 0x23000
	v_lshl_add_u32 v235, s91, 10, v235
	v_lshl_add_u32 v231, v233, 4, v235
	v_and_b32_e32 v230, 15, v233
	v_lshrrev_b32_e32 v232, 1, v230
	v_lshrrev_b32_e32 v234, 4, v233
	v_xor_b32_e32 v232, v232, v234
	v_and_b32_e32 v232, 3, v232
	v_lshlrev_b32_e32 v232, 4, v232
	v_lshl_add_u32 v230, v230, 6, v232
	v_add_u32_e32 v230, v235, v230
	v_mov_b32_e32 v139, v135
	v_add_u32_e32 v140, v0, v11
	v_mov_b32_e32 v141, v135
	v_mov_b64_e32 v[142:143], 0xb00
	v_mov_b64_e32 v[144:145], 0xaff
	v_add_u32_e32 v153, s47, v150
	v_add_u32_e32 v154, s48, v150
	v_add_u32_e32 v155, 0, v2
	s_movk_i32 s49, 0x1600
	s_mov_b32 s50, 0
	s_barrier
	s_branch .LBB0_2088

.LBB0_2094:
	v_lshl_add_u32 v157, s12, 10, v151
	ds_read_b32 v158, v157
	v_lshl_or_b32 v148, s13, 7, v152
	v_lshl_add_u32 v156, s24, 8, v129
	v_ashrrev_i32_e32 v149, 31, v148
	v_mov_b64_e32 v[146:147], s[16:17]
	s_waitcnt lgkmcnt(0)
	v_pk_mul_f32 v[124:125], v[124:125], v[158:159] op_sel_hi:[1,0]
	v_pk_mul_f32 v[126:127], v[126:127], v[158:159] op_sel_hi:[1,0]
	v_pk_mul_f32 v[122:123], v[122:123], v[158:159] op_sel_hi:[1,0]
	v_pk_mul_f32 v[120:121], v[120:121], v[158:159] op_sel_hi:[1,0]
	v_pk_mul_f32 v[118:119], v[118:119], v[158:159] op_sel_hi:[1,0]
	v_pk_mul_f32 v[116:117], v[116:117], v[158:159] op_sel_hi:[1,0]
	v_mul_f32_e32 v159, 0xbfb8aa3b, v124
	v_exp_f32_e32 v159, v159
	v_mul_f32_e32 v162, 0xbfb8aa3b, v125
	v_exp_f32_e32 v164, v162
	v_mad_i64_i32 v[160:161], s[12:13], v156, s49, v[146:147]
	v_pk_mul_f32 v[162:163], v[114:115], v[158:159] op_sel_hi:[1,0]
	v_add_f32_e32 v114, 1.0, v159
	v_rcp_f32_e32 v159, v114
	v_add_f32_e32 v114, 1.0, v164
	v_rcp_f32_e32 v164, v114
	v_lshlrev_b64 v[148:149], 1, v[148:149]
	v_pk_mul_f32 v[114:115], v[112:113], v[158:159] op_sel_hi:[1,0]
	v_mul_f32_e32 v112, v124, v159
	v_mul_f32_e32 v112, v116, v112
	v_mul_f32_e32 v116, 0xbfb8aa3b, v126
	v_mul_f32_e32 v124, 0xbfb8aa3b, v127
	v_exp_f32_e32 v116, v116
	v_exp_f32_e32 v124, v124
	v_mul_f32_e32 v113, v125, v164
	v_mul_f32_e32 v113, v117, v113
	v_add_f32_e32 v116, 1.0, v116
	v_add_f32_e32 v117, 1.0, v124
	v_rcp_f32_e32 v116, v116
	v_rcp_f32_e32 v117, v117
	v_cvt_pk_bf16_f32 v112, v112, v113
	v_lshl_add_u64 v[160:161], v[160:161], 0, v[148:149]
	v_mul_f32_e32 v113, v126, v116
	v_mul_f32_e32 v116, v127, v117
	v_mul_f32_e32 v117, 0xbfb8aa3b, v120
	v_mul_f32_e32 v113, v118, v113
	v_exp_f32_e32 v117, v117
	v_mul_f32_e32 v118, 0xbfb8aa3b, v121
	v_exp_f32_e32 v118, v118
	v_mul_f32_e32 v116, v119, v116
	v_add_f32_e32 v117, 1.0, v117
	v_rcp_f32_e32 v117, v117
	v_add_f32_e32 v118, 1.0, v118
	v_rcp_f32_e32 v118, v118
	v_cvt_pk_bf16_f32 v113, v113, v116
	v_mul_f32_e32 v116, v120, v117
	v_mul_f32_e32 v117, 0xbfb8aa3b, v122
	v_mul_f32_e32 v114, v114, v116
	v_mul_f32_e32 v116, v121, v118
	v_exp_f32_e32 v117, v117
	v_mul_f32_e32 v118, 0xbfb8aa3b, v123
	v_exp_f32_e32 v118, v118
	v_mul_f32_e32 v115, v115, v116
	v_add_f32_e32 v116, 1.0, v117
	v_rcp_f32_e32 v116, v116
	v_add_f32_e32 v117, 1.0, v118
	v_rcp_f32_e32 v117, v117
	v_cvt_pk_bf16_f32 v114, v114, v115
	v_mul_f32_e32 v115, v122, v116
	v_mul_f32_e32 v115, v162, v115
	v_mul_f32_e32 v116, v123, v117
	v_mul_f32_e32 v116, v163, v116
	v_cvt_pk_bf16_f32 v115, v115, v116
	ds_write_b128 v230, v[112:115]
	ds_read_b128 v[232:235], v231
	v_mov_b32_e32 v236, v160
	v_mov_b32_e32 v237, v161
	ds_read_b32 v112, v157 offset:64
	s_andn2_b64 vcc, exec, s[4:5]
	v_or_b32_e32 v113, 16, v156
	v_mad_i64_i32 v[114:115], s[12:13], v113, s49, v[146:147]
	s_waitcnt lgkmcnt(0)
	global_store_dwordx4 v[236:237], v[232:235], off
	v_pk_mul_f32 v[108:109], v[108:109], v[112:113] op_sel_hi:[1,0]
	v_pk_mul_f32 v[110:111], v[110:111], v[112:113] op_sel_hi:[1,0]
	v_pk_mul_f32 v[106:107], v[106:107], v[112:113] op_sel_hi:[1,0]
	v_pk_mul_f32 v[104:105], v[104:105], v[112:113] op_sel_hi:[1,0]
	v_pk_mul_f32 v[102:103], v[102:103], v[112:113] op_sel_hi:[1,0]
	v_pk_mul_f32 v[100:101], v[100:101], v[112:113] op_sel_hi:[1,0]
	v_mul_f32_e32 v113, 0xbfb8aa3b, v108
	v_exp_f32_e32 v113, v113
	v_mul_f32_e32 v116, 0xbfb8aa3b, v109
	v_exp_f32_e32 v118, v116
	v_lshl_add_u64 v[114:115], v[114:115], 0, v[148:149]
	v_pk_mul_f32 v[116:117], v[98:99], v[112:113] op_sel_hi:[1,0]
	v_add_f32_e32 v98, 1.0, v113
	v_rcp_f32_e32 v113, v98
	v_add_f32_e32 v98, 1.0, v118
	v_rcp_f32_e32 v118, v98
	s_mov_b64 s[4:5], -1
	v_pk_mul_f32 v[98:99], v[96:97], v[112:113] op_sel_hi:[1,0]
	v_mul_f32_e32 v96, v108, v113
	v_mul_f32_e32 v96, v100, v96
	v_mul_f32_e32 v100, 0xbfb8aa3b, v110
	v_mul_f32_e32 v108, 0xbfb8aa3b, v111
	v_exp_f32_e32 v100, v100
	v_exp_f32_e32 v108, v108
	v_mul_f32_e32 v97, v109, v118
	v_mul_f32_e32 v97, v101, v97
	v_add_f32_e32 v100, 1.0, v100
	v_add_f32_e32 v101, 1.0, v108
	v_rcp_f32_e32 v100, v100
	v_rcp_f32_e32 v101, v101
	v_cvt_pk_bf16_f32 v96, v96, v97
	v_mul_f32_e32 v97, v110, v100
	v_mul_f32_e32 v100, v111, v101
	v_mul_f32_e32 v101, 0xbfb8aa3b, v104
	v_mul_f32_e32 v97, v102, v97
	v_exp_f32_e32 v101, v101
	v_mul_f32_e32 v102, 0xbfb8aa3b, v105
	v_exp_f32_e32 v102, v102
	v_mul_f32_e32 v100, v103, v100
	v_add_f32_e32 v101, 1.0, v101
	v_rcp_f32_e32 v101, v101
	v_add_f32_e32 v102, 1.0, v102
	v_rcp_f32_e32 v102, v102
	v_cvt_pk_bf16_f32 v97, v97, v100
	v_mul_f32_e32 v100, v104, v101
	v_mul_f32_e32 v101, 0xbfb8aa3b, v106
	v_mul_f32_e32 v98, v98, v100
	v_mul_f32_e32 v100, v105, v102
	v_exp_f32_e32 v101, v101
	v_mul_f32_e32 v102, 0xbfb8aa3b, v107
	v_exp_f32_e32 v102, v102
	v_mul_f32_e32 v99, v99, v100
	v_add_f32_e32 v100, 1.0, v101
	v_rcp_f32_e32 v100, v100
	v_add_f32_e32 v101, 1.0, v102
	v_rcp_f32_e32 v101, v101
	v_cvt_pk_bf16_f32 v98, v98, v99
	v_mul_f32_e32 v99, v106, v100
	v_mul_f32_e32 v99, v116, v99
	v_mul_f32_e32 v100, v107, v101
	v_mul_f32_e32 v100, v117, v100
	v_cvt_pk_bf16_f32 v99, v99, v100
	ds_write_b128 v230, v[96:99]
	ds_read_b128 v[232:235], v231
	v_mov_b32_e32 v236, v114
	v_mov_b32_e32 v237, v115
	ds_read_b32 v96, v157 offset:128
	s_nop 0
	v_or_b32_e32 v97, 32, v156
	v_mad_i64_i32 v[98:99], s[12:13], v97, s49, v[146:147]
	s_waitcnt lgkmcnt(0)
	global_store_dwordx4 v[236:237], v[232:235], off
	v_pk_mul_f32 v[92:93], v[92:93], v[96:97] op_sel_hi:[1,0]
	v_pk_mul_f32 v[94:95], v[94:95], v[96:97] op_sel_hi:[1,0]
	v_pk_mul_f32 v[90:91], v[90:91], v[96:97] op_sel_hi:[1,0]
	v_pk_mul_f32 v[88:89], v[88:89], v[96:97] op_sel_hi:[1,0]
	v_pk_mul_f32 v[86:87], v[86:87], v[96:97] op_sel_hi:[1,0]
	v_pk_mul_f32 v[84:85], v[84:85], v[96:97] op_sel_hi:[1,0]
	v_mul_f32_e32 v97, 0xbfb8aa3b, v92
	v_exp_f32_e32 v97, v97
	v_mul_f32_e32 v100, 0xbfb8aa3b, v93
	v_exp_f32_e32 v102, v100
	v_lshl_add_u64 v[98:99], v[98:99], 0, v[148:149]
	v_pk_mul_f32 v[100:101], v[82:83], v[96:97] op_sel_hi:[1,0]
	v_add_f32_e32 v82, 1.0, v97
	v_rcp_f32_e32 v97, v82
	v_add_f32_e32 v82, 1.0, v102
	v_rcp_f32_e32 v102, v82
	v_pk_mul_f32 v[82:83], v[80:81], v[96:97] op_sel_hi:[1,0]
	v_mul_f32_e32 v80, v92, v97
	v_mul_f32_e32 v80, v84, v80
	v_mul_f32_e32 v84, 0xbfb8aa3b, v94
	v_mul_f32_e32 v92, 0xbfb8aa3b, v95
	v_exp_f32_e32 v84, v84
	v_exp_f32_e32 v92, v92
	v_mul_f32_e32 v81, v93, v102
	v_mul_f32_e32 v81, v85, v81
	v_add_f32_e32 v84, 1.0, v84
	v_add_f32_e32 v85, 1.0, v92
	v_rcp_f32_e32 v84, v84
	v_rcp_f32_e32 v85, v85
	v_cvt_pk_bf16_f32 v80, v80, v81
	v_mul_f32_e32 v81, v94, v84
	v_mul_f32_e32 v84, v95, v85
	v_mul_f32_e32 v85, 0xbfb8aa3b, v88
	v_mul_f32_e32 v81, v86, v81
	v_exp_f32_e32 v85, v85
	v_mul_f32_e32 v86, 0xbfb8aa3b, v89
	v_exp_f32_e32 v86, v86
	v_mul_f32_e32 v84, v87, v84
	v_add_f32_e32 v85, 1.0, v85
	v_rcp_f32_e32 v85, v85
	v_add_f32_e32 v86, 1.0, v86
	v_rcp_f32_e32 v86, v86
	v_cvt_pk_bf16_f32 v81, v81, v84
	v_mul_f32_e32 v84, v88, v85
	v_mul_f32_e32 v85, 0xbfb8aa3b, v90
	v_mul_f32_e32 v82, v82, v84
	v_mul_f32_e32 v84, v89, v86
	v_exp_f32_e32 v85, v85
	v_mul_f32_e32 v86, 0xbfb8aa3b, v91
	v_exp_f32_e32 v86, v86
	v_mul_f32_e32 v83, v83, v84
	v_add_f32_e32 v84, 1.0, v85
	v_rcp_f32_e32 v84, v84
	v_add_f32_e32 v85, 1.0, v86
	v_rcp_f32_e32 v85, v85
	v_cvt_pk_bf16_f32 v82, v82, v83
	v_mul_f32_e32 v83, v90, v84
	v_mul_f32_e32 v83, v100, v83
	v_mul_f32_e32 v84, v91, v85
	v_mul_f32_e32 v84, v101, v84
	v_cvt_pk_bf16_f32 v83, v83, v84
	ds_write_b128 v230, v[80:83]
	ds_read_b128 v[232:235], v231
	v_mov_b32_e32 v236, v98
	v_mov_b32_e32 v237, v99
	ds_read_b32 v80, v157 offset:192
	s_nop 0
	v_or_b32_e32 v81, 48, v156
	v_mad_i64_i32 v[82:83], s[12:13], v81, s49, v[146:147]
	s_waitcnt lgkmcnt(0)
	global_store_dwordx4 v[236:237], v[232:235], off
	v_pk_mul_f32 v[76:77], v[76:77], v[80:81] op_sel_hi:[1,0]
	v_pk_mul_f32 v[78:79], v[78:79], v[80:81] op_sel_hi:[1,0]
	v_pk_mul_f32 v[74:75], v[74:75], v[80:81] op_sel_hi:[1,0]
	v_pk_mul_f32 v[72:73], v[72:73], v[80:81] op_sel_hi:[1,0]
	v_pk_mul_f32 v[70:71], v[70:71], v[80:81] op_sel_hi:[1,0]
	v_pk_mul_f32 v[68:69], v[68:69], v[80:81] op_sel_hi:[1,0]
	v_mul_f32_e32 v81, 0xbfb8aa3b, v76
	v_exp_f32_e32 v81, v81
	v_mul_f32_e32 v84, 0xbfb8aa3b, v77
	v_exp_f32_e32 v86, v84
	v_lshl_add_u64 v[82:83], v[82:83], 0, v[148:149]
	v_pk_mul_f32 v[84:85], v[66:67], v[80:81] op_sel_hi:[1,0]
	v_add_f32_e32 v66, 1.0, v81
	v_rcp_f32_e32 v81, v66
	v_add_f32_e32 v66, 1.0, v86
	v_rcp_f32_e32 v86, v66
	v_pk_mul_f32 v[66:67], v[64:65], v[80:81] op_sel_hi:[1,0]
	v_mul_f32_e32 v64, v76, v81
	v_mul_f32_e32 v64, v68, v64
	v_mul_f32_e32 v68, 0xbfb8aa3b, v78
	v_mul_f32_e32 v76, 0xbfb8aa3b, v79
	v_exp_f32_e32 v68, v68
	v_exp_f32_e32 v76, v76
	v_mul_f32_e32 v65, v77, v86
	v_mul_f32_e32 v65, v69, v65
	v_add_f32_e32 v68, 1.0, v68
	v_add_f32_e32 v69, 1.0, v76
	v_rcp_f32_e32 v68, v68
	v_rcp_f32_e32 v69, v69
	v_cvt_pk_bf16_f32 v64, v64, v65
	v_mul_f32_e32 v65, v78, v68
	v_mul_f32_e32 v68, v79, v69
	v_mul_f32_e32 v69, 0xbfb8aa3b, v72
	v_mul_f32_e32 v65, v70, v65
	v_exp_f32_e32 v69, v69
	v_mul_f32_e32 v70, 0xbfb8aa3b, v73
	v_exp_f32_e32 v70, v70
	v_mul_f32_e32 v68, v71, v68
	v_add_f32_e32 v69, 1.0, v69
	v_rcp_f32_e32 v69, v69
	v_add_f32_e32 v70, 1.0, v70
	v_rcp_f32_e32 v70, v70
	v_cvt_pk_bf16_f32 v65, v65, v68
	v_mul_f32_e32 v68, v72, v69
	v_mul_f32_e32 v69, 0xbfb8aa3b, v74
	v_mul_f32_e32 v66, v66, v68
	v_mul_f32_e32 v68, v73, v70
	v_exp_f32_e32 v69, v69
	v_mul_f32_e32 v70, 0xbfb8aa3b, v75
	v_exp_f32_e32 v70, v70
	v_mul_f32_e32 v67, v67, v68
	v_add_f32_e32 v68, 1.0, v69
	v_rcp_f32_e32 v68, v68
	v_add_f32_e32 v69, 1.0, v70
	v_rcp_f32_e32 v69, v69
	v_cvt_pk_bf16_f32 v66, v66, v67
	v_mul_f32_e32 v67, v74, v68
	v_mul_f32_e32 v67, v84, v67
	v_mul_f32_e32 v68, v75, v69
	v_mul_f32_e32 v68, v85, v68
	v_cvt_pk_bf16_f32 v67, v67, v68
	ds_write_b128 v230, v[64:67]
	ds_read_b128 v[232:235], v231
	v_mov_b32_e32 v236, v82
	v_mov_b32_e32 v237, v83
	ds_read_b32 v64, v157 offset:512
	s_nop 0
	v_add_u32_e32 v65, 0x80, v156
	v_mad_i64_i32 v[66:67], s[12:13], v65, s49, v[146:147]
	s_waitcnt lgkmcnt(0)
	global_store_dwordx4 v[236:237], v[232:235], off
	v_pk_mul_f32 v[60:61], v[60:61], v[64:65] op_sel_hi:[1,0]
	v_pk_mul_f32 v[62:63], v[62:63], v[64:65] op_sel_hi:[1,0]
	v_pk_mul_f32 v[58:59], v[58:59], v[64:65] op_sel_hi:[1,0]
	v_pk_mul_f32 v[56:57], v[56:57], v[64:65] op_sel_hi:[1,0]
	v_pk_mul_f32 v[54:55], v[54:55], v[64:65] op_sel_hi:[1,0]
	v_pk_mul_f32 v[52:53], v[52:53], v[64:65] op_sel_hi:[1,0]
	v_mul_f32_e32 v65, 0xbfb8aa3b, v60
	v_exp_f32_e32 v65, v65
	v_mul_f32_e32 v68, 0xbfb8aa3b, v61
	v_exp_f32_e32 v70, v68
	v_lshl_add_u64 v[66:67], v[66:67], 0, v[148:149]
	v_pk_mul_f32 v[68:69], v[50:51], v[64:65] op_sel_hi:[1,0]
	v_add_f32_e32 v50, 1.0, v65
	v_rcp_f32_e32 v65, v50
	v_add_f32_e32 v50, 1.0, v70
	v_rcp_f32_e32 v70, v50
	v_pk_mul_f32 v[50:51], v[48:49], v[64:65] op_sel_hi:[1,0]
	v_mul_f32_e32 v48, v60, v65
	v_mul_f32_e32 v48, v52, v48
	v_mul_f32_e32 v52, 0xbfb8aa3b, v62
	v_mul_f32_e32 v60, 0xbfb8aa3b, v63
	v_exp_f32_e32 v52, v52
	v_exp_f32_e32 v60, v60
	v_mul_f32_e32 v49, v61, v70
	v_mul_f32_e32 v49, v53, v49
	v_add_f32_e32 v52, 1.0, v52
	v_add_f32_e32 v53, 1.0, v60
	v_rcp_f32_e32 v52, v52
	v_rcp_f32_e32 v53, v53
	v_cvt_pk_bf16_f32 v48, v48, v49
	v_mul_f32_e32 v49, v62, v52
	v_mul_f32_e32 v52, v63, v53
	v_mul_f32_e32 v53, 0xbfb8aa3b, v56
	v_mul_f32_e32 v49, v54, v49
	v_exp_f32_e32 v53, v53
	v_mul_f32_e32 v54, 0xbfb8aa3b, v57
	v_exp_f32_e32 v54, v54
	v_mul_f32_e32 v52, v55, v52
	v_add_f32_e32 v53, 1.0, v53
	v_rcp_f32_e32 v53, v53
	v_add_f32_e32 v54, 1.0, v54
	v_rcp_f32_e32 v54, v54
	v_cvt_pk_bf16_f32 v49, v49, v52
	v_mul_f32_e32 v52, v56, v53
	v_mul_f32_e32 v53, 0xbfb8aa3b, v58
	v_mul_f32_e32 v50, v50, v52
	v_mul_f32_e32 v52, v57, v54
	v_exp_f32_e32 v53, v53
	v_mul_f32_e32 v54, 0xbfb8aa3b, v59
	v_exp_f32_e32 v54, v54
	v_mul_f32_e32 v51, v51, v52
	v_add_f32_e32 v52, 1.0, v53
	v_rcp_f32_e32 v52, v52
	v_add_f32_e32 v53, 1.0, v54
	v_rcp_f32_e32 v53, v53
	v_cvt_pk_bf16_f32 v50, v50, v51
	v_mul_f32_e32 v51, v58, v52
	v_mul_f32_e32 v51, v68, v51
	v_mul_f32_e32 v52, v59, v53
	v_mul_f32_e32 v52, v69, v52
	v_cvt_pk_bf16_f32 v51, v51, v52
	ds_write_b128 v230, v[48:51]
	ds_read_b128 v[232:235], v231
	v_mov_b32_e32 v236, v66
	v_mov_b32_e32 v237, v67
	ds_read_b32 v48, v157 offset:576
	s_nop 0
	v_add_u32_e32 v49, 0x90, v156
	v_mad_i64_i32 v[50:51], s[12:13], v49, s49, v[146:147]
	s_waitcnt lgkmcnt(0)
	global_store_dwordx4 v[236:237], v[232:235], off
	v_pk_mul_f32 v[44:45], v[44:45], v[48:49] op_sel_hi:[1,0]
	v_pk_mul_f32 v[46:47], v[46:47], v[48:49] op_sel_hi:[1,0]
	v_pk_mul_f32 v[42:43], v[42:43], v[48:49] op_sel_hi:[1,0]
	v_pk_mul_f32 v[40:41], v[40:41], v[48:49] op_sel_hi:[1,0]
	v_pk_mul_f32 v[38:39], v[38:39], v[48:49] op_sel_hi:[1,0]
	v_pk_mul_f32 v[36:37], v[36:37], v[48:49] op_sel_hi:[1,0]
	v_mul_f32_e32 v49, 0xbfb8aa3b, v44
	v_exp_f32_e32 v49, v49
	v_mul_f32_e32 v52, 0xbfb8aa3b, v45
	v_exp_f32_e32 v54, v52
	v_lshl_add_u64 v[50:51], v[50:51], 0, v[148:149]
	v_pk_mul_f32 v[52:53], v[34:35], v[48:49] op_sel_hi:[1,0]
	v_add_f32_e32 v34, 1.0, v49
	v_rcp_f32_e32 v49, v34
	v_add_f32_e32 v34, 1.0, v54
	v_rcp_f32_e32 v54, v34
	v_pk_mul_f32 v[34:35], v[32:33], v[48:49] op_sel_hi:[1,0]
	v_mul_f32_e32 v32, v44, v49
	v_mul_f32_e32 v32, v36, v32
	v_mul_f32_e32 v36, 0xbfb8aa3b, v46
	v_mul_f32_e32 v44, 0xbfb8aa3b, v47
	v_exp_f32_e32 v36, v36
	v_exp_f32_e32 v44, v44
	v_mul_f32_e32 v33, v45, v54
	v_mul_f32_e32 v33, v37, v33
	v_add_f32_e32 v36, 1.0, v36
	v_add_f32_e32 v37, 1.0, v44
	v_rcp_f32_e32 v36, v36
	v_rcp_f32_e32 v37, v37
	v_cvt_pk_bf16_f32 v32, v32, v33
	v_mul_f32_e32 v33, v46, v36
	v_mul_f32_e32 v36, v47, v37
	v_mul_f32_e32 v37, 0xbfb8aa3b, v40
	v_mul_f32_e32 v33, v38, v33
	v_exp_f32_e32 v37, v37
	v_mul_f32_e32 v38, 0xbfb8aa3b, v41
	v_exp_f32_e32 v38, v38
	v_mul_f32_e32 v36, v39, v36
	v_add_f32_e32 v37, 1.0, v37
	v_rcp_f32_e32 v37, v37
	v_add_f32_e32 v38, 1.0, v38
	v_rcp_f32_e32 v38, v38
	v_cvt_pk_bf16_f32 v33, v33, v36
	v_mul_f32_e32 v36, v40, v37
	v_mul_f32_e32 v37, 0xbfb8aa3b, v42
	v_mul_f32_e32 v34, v34, v36
	v_mul_f32_e32 v36, v41, v38
	v_exp_f32_e32 v37, v37
	v_mul_f32_e32 v38, 0xbfb8aa3b, v43
	v_exp_f32_e32 v38, v38
	v_mul_f32_e32 v35, v35, v36
	v_add_f32_e32 v36, 1.0, v37
	v_rcp_f32_e32 v36, v36
	v_add_f32_e32 v37, 1.0, v38
	v_rcp_f32_e32 v37, v37
	v_cvt_pk_bf16_f32 v34, v34, v35
	v_mul_f32_e32 v35, v42, v36
	v_mul_f32_e32 v35, v52, v35
	v_mul_f32_e32 v36, v43, v37
	v_mul_f32_e32 v36, v53, v36
	v_cvt_pk_bf16_f32 v35, v35, v36
	ds_write_b128 v230, v[32:35]
	ds_read_b128 v[232:235], v231
	v_mov_b32_e32 v236, v50
	v_mov_b32_e32 v237, v51
	ds_read_b32 v32, v157 offset:640
	s_nop 0
	v_add_u32_e32 v33, 0xa0, v156
	v_mad_i64_i32 v[34:35], s[12:13], v33, s49, v[146:147]
	s_waitcnt lgkmcnt(0)
	global_store_dwordx4 v[236:237], v[232:235], off
	v_pk_mul_f32 v[28:29], v[28:29], v[32:33] op_sel_hi:[1,0]
	v_pk_mul_f32 v[30:31], v[30:31], v[32:33] op_sel_hi:[1,0]
	v_pk_mul_f32 v[26:27], v[26:27], v[32:33] op_sel_hi:[1,0]
	v_pk_mul_f32 v[24:25], v[24:25], v[32:33] op_sel_hi:[1,0]
	v_pk_mul_f32 v[22:23], v[22:23], v[32:33] op_sel_hi:[1,0]
	v_pk_mul_f32 v[20:21], v[20:21], v[32:33] op_sel_hi:[1,0]
	v_mul_f32_e32 v33, 0xbfb8aa3b, v28
	v_exp_f32_e32 v33, v33
	v_mul_f32_e32 v36, 0xbfb8aa3b, v29
	v_exp_f32_e32 v38, v36
	v_lshl_add_u64 v[34:35], v[34:35], 0, v[148:149]
	v_pk_mul_f32 v[36:37], v[18:19], v[32:33] op_sel_hi:[1,0]
	v_add_f32_e32 v18, 1.0, v33
	v_rcp_f32_e32 v33, v18
	v_add_f32_e32 v18, 1.0, v38
	v_rcp_f32_e32 v38, v18
	v_pk_mul_f32 v[18:19], v[16:17], v[32:33] op_sel_hi:[1,0]
	v_mul_f32_e32 v16, v28, v33
	v_mul_f32_e32 v16, v20, v16
	v_mul_f32_e32 v20, 0xbfb8aa3b, v30
	v_mul_f32_e32 v28, 0xbfb8aa3b, v31
	v_exp_f32_e32 v20, v20
	v_exp_f32_e32 v28, v28
	v_mul_f32_e32 v17, v29, v38
	v_mul_f32_e32 v17, v21, v17
	v_add_f32_e32 v20, 1.0, v20
	v_add_f32_e32 v21, 1.0, v28
	v_rcp_f32_e32 v20, v20
	v_rcp_f32_e32 v21, v21
	v_cvt_pk_bf16_f32 v16, v16, v17
	v_mul_f32_e32 v17, v30, v20
	v_mul_f32_e32 v20, v31, v21
	v_mul_f32_e32 v21, 0xbfb8aa3b, v24
	v_mul_f32_e32 v17, v22, v17
	v_exp_f32_e32 v21, v21
	v_mul_f32_e32 v22, 0xbfb8aa3b, v25
	v_exp_f32_e32 v22, v22
	v_mul_f32_e32 v20, v23, v20
	v_add_f32_e32 v21, 1.0, v21
	v_rcp_f32_e32 v21, v21
	v_add_f32_e32 v22, 1.0, v22
	v_rcp_f32_e32 v22, v22
	v_cvt_pk_bf16_f32 v17, v17, v20
	v_mul_f32_e32 v20, v24, v21
	v_mul_f32_e32 v21, 0xbfb8aa3b, v26
	v_mul_f32_e32 v18, v18, v20
	v_mul_f32_e32 v20, v25, v22
	v_exp_f32_e32 v21, v21
	v_mul_f32_e32 v22, 0xbfb8aa3b, v27
	v_exp_f32_e32 v22, v22
	v_mul_f32_e32 v19, v19, v20
	v_add_f32_e32 v20, 1.0, v21
	v_rcp_f32_e32 v20, v20
	v_add_f32_e32 v21, 1.0, v22
	v_rcp_f32_e32 v21, v21
	v_cvt_pk_bf16_f32 v18, v18, v19
	v_mul_f32_e32 v19, v26, v20
	v_mul_f32_e32 v19, v36, v19
	v_mul_f32_e32 v20, v27, v21
	v_mul_f32_e32 v20, v37, v20
	v_cvt_pk_bf16_f32 v19, v19, v20
	ds_write_b128 v230, v[16:19]
	ds_read_b128 v[232:235], v231
	v_mov_b32_e32 v236, v34
	v_mov_b32_e32 v237, v35
	ds_read_b32 v16, v157 offset:704
	s_nop 0
	v_add_u32_e32 v17, 0xb0, v156
	v_mad_i64_i32 v[18:19], s[12:13], v17, s49, v[146:147]
	s_waitcnt lgkmcnt(0)
	global_store_dwordx4 v[236:237], v[232:235], off
	v_pk_mul_f32 v[12:13], v[12:13], v[16:17] op_sel_hi:[1,0]
	v_pk_mul_f32 v[14:15], v[14:15], v[16:17] op_sel_hi:[1,0]
	v_pk_mul_f32 v[10:11], v[10:11], v[16:17] op_sel_hi:[1,0]
	v_pk_mul_f32 v[8:9], v[8:9], v[16:17] op_sel_hi:[1,0]
	v_pk_mul_f32 v[6:7], v[6:7], v[16:17] op_sel_hi:[1,0]
	v_pk_mul_f32 v[4:5], v[4:5], v[16:17] op_sel_hi:[1,0]
	v_mul_f32_e32 v17, 0xbfb8aa3b, v12
	v_exp_f32_e32 v17, v17
	v_mul_f32_e32 v20, 0xbfb8aa3b, v13
	v_exp_f32_e32 v22, v20
	v_lshl_add_u64 v[18:19], v[18:19], 0, v[148:149]
	v_pk_mul_f32 v[20:21], v[2:3], v[16:17] op_sel_hi:[1,0]
	v_add_f32_e32 v2, 1.0, v17
	v_rcp_f32_e32 v17, v2
	v_add_f32_e32 v2, 1.0, v22
	v_rcp_f32_e32 v22, v2
	v_pk_mul_f32 v[2:3], v[0:1], v[16:17] op_sel_hi:[1,0]
	v_mul_f32_e32 v0, v12, v17
	v_mul_f32_e32 v0, v4, v0
	v_mul_f32_e32 v4, 0xbfb8aa3b, v14
	v_mul_f32_e32 v12, 0xbfb8aa3b, v15
	v_exp_f32_e32 v4, v4
	v_exp_f32_e32 v12, v12
	v_mul_f32_e32 v1, v13, v22
	v_mul_f32_e32 v1, v5, v1
	v_add_f32_e32 v4, 1.0, v4
	v_add_f32_e32 v5, 1.0, v12
	v_rcp_f32_e32 v4, v4
	v_rcp_f32_e32 v5, v5
	v_cvt_pk_bf16_f32 v0, v0, v1
	v_mul_f32_e32 v1, v14, v4
	v_mul_f32_e32 v4, v15, v5
	v_mul_f32_e32 v5, 0xbfb8aa3b, v8
	v_mul_f32_e32 v1, v6, v1
	v_exp_f32_e32 v5, v5
	v_mul_f32_e32 v6, 0xbfb8aa3b, v9
	v_exp_f32_e32 v6, v6
	v_mul_f32_e32 v4, v7, v4
	v_add_f32_e32 v5, 1.0, v5
	v_rcp_f32_e32 v5, v5
	v_add_f32_e32 v6, 1.0, v6
	v_rcp_f32_e32 v6, v6
	v_cvt_pk_bf16_f32 v1, v1, v4
	v_mul_f32_e32 v4, v8, v5
	v_mul_f32_e32 v5, 0xbfb8aa3b, v10
	v_mul_f32_e32 v2, v2, v4
	v_mul_f32_e32 v4, v9, v6
	v_exp_f32_e32 v5, v5
	v_mul_f32_e32 v6, 0xbfb8aa3b, v11
	v_exp_f32_e32 v6, v6
	v_mul_f32_e32 v3, v3, v4
	v_add_f32_e32 v4, 1.0, v5
	v_rcp_f32_e32 v4, v4
	v_add_f32_e32 v5, 1.0, v6
	v_rcp_f32_e32 v5, v5
	v_cvt_pk_bf16_f32 v2, v2, v3
	v_mul_f32_e32 v3, v10, v4
	v_mul_f32_e32 v3, v20, v3
	v_mul_f32_e32 v4, v11, v5
	v_mul_f32_e32 v4, v21, v4
	v_cvt_pk_bf16_f32 v3, v3, v4
	ds_write_b128 v230, v[0:3]
	ds_read_b128 v[232:235], v231
	v_mov_b32_e32 v236, v18
	v_mov_b32_e32 v237, v19
	s_waitcnt lgkmcnt(0)
	global_store_dwordx4 v[236:237], v[232:235], off
	s_cbranch_vccnz .LBB0_2087
	s_andn2_b64 vcc, exec, s[0:1]
	s_cbranch_vccnz .LBB0_2086
	s_nop 0
	s_branch .LBB0_2086
